# write-through only on GEMM-epilogue and final-phase dwordx4 stores (weight-conversion stores left write-back)
# baseline (speedup 1.0000x reference)
; #define LAS __attribute__((address_space(3)))
; __device__ __forceinline__ unsigned cvtpk(float lo, float hi) { f32x2 v = {lo, hi}; bf16x2_t b = __builtin_convertvector(v, bf16x2_t); return __builtin_bit_cast(unsigned, b); }
; __device__ __forceinline__ void witem_store(const WItem& w, int K, bf16_t* WT, int kvperm, LAS float* scr, int item, int nblk, int lane) {
;     const int kb = item / nblk, nb = item % nblk, k0 = 64 * kb, n0 = 32 * nb;
;     const int col = 4 * (lane & 7), rr = lane >> 3;
; #pragma unroll
;     for (int i = 0; i < 8; ++i) { LAS float* d = scr + (8 * i + rr) * 33 + col; const float g = w.g[i]; d[0] = w.v[i].x * g; d[1] = w.v[i].y * g; d[2] = w.v[i].z * g; d[3] = w.v[i].w * g; }
;     asm volatile("s_waitcnt lgkmcnt(0)" ::: "memory");
;     const int c = lane & 7;
; #pragma unroll
;     for (int j = 0; j < 4; ++j) { const int n = (lane >> 3) + 8 * j; const LAS float* s = scr + (8 * c) * 33 + n;
;         u32x4 o; o.x = cvtpk(s[0 * 33], s[1 * 33]); o.y = cvtpk(s[2 * 33], s[3 * 33]); o.z = cvtpk(s[4 * 33], s[5 * 33]); o.w = cvtpk(s[6 * 33], s[7 * 33]);
;         int nr = n0 + n; if (kvperm == 1) { const int hh = nr >> 8, ww = nr & 255; nr = (ww < 128) ? hh * 128 + ww : 2048 + hh * 128 + (ww - 128); }
;         else if (kvperm == 2) { const int isv = nr >= 5632, f = isv ? nr - 5632 : nr; nr = (f >> 7) * 256 + isv * 128 + (f & 127); }
;         *(u32x4*)(WT + (size_t)nr * K + k0 + 8 * c) = o; }
.LBB0_382:
	v_pk_mul_f32 v[2:3], v[2:3], v[72:73] op_sel_hi:[1,0]
	ds_write2_b32 v79, v2, v3 offset1:1
	v_pk_mul_f32 v[2:3], v[4:5], v[72:73] op_sel_hi:[1,0]
	ds_write2_b32 v79, v2, v3 offset0:2 offset1:3
	v_pk_mul_f32 v[2:3], v[6:7], v[74:75] op_sel_hi:[1,0]
	v_add_u32_e32 v4, 0x420, v79
	ds_write2_b32 v4, v2, v3 offset1:1
	v_pk_mul_f32 v[2:3], v[8:9], v[74:75] op_sel_hi:[1,0]
	v_add_u32_e32 v4, 0x428, v79
	ds_write2_b32 v4, v2, v3 offset1:1
	v_pk_mul_f32 v[2:3], v[10:11], v[76:77] op_sel_hi:[1,0]
	v_add_u32_e32 v4, 0x840, v79
	ds_write2_b32 v4, v2, v3 offset1:1
	v_pk_mul_f32 v[2:3], v[12:13], v[76:77] op_sel_hi:[1,0]
	v_add_u32_e32 v4, 0x848, v79
	ds_write2_b32 v4, v2, v3 offset1:1
	v_pk_mul_f32 v[2:3], v[14:15], v[78:79] op_sel_hi:[1,0]
	v_add_u32_e32 v4, 0xc60, v79
	ds_write2_b32 v4, v2, v3 offset1:1
	v_pk_mul_f32 v[2:3], v[16:17], v[78:79] op_sel_hi:[1,0]
	v_add_u32_e32 v4, 0xc68, v79
	ds_write2_b32 v4, v2, v3 offset1:1
	v_pk_mul_f32 v[2:3], v[18:19], v[84:85] op_sel_hi:[1,0]
	v_add_u32_e32 v4, 0x1080, v79
	ds_write2_b32 v4, v2, v3 offset1:1
	v_pk_mul_f32 v[2:3], v[20:21], v[84:85] op_sel_hi:[1,0]
	v_add_u32_e32 v4, 0x1088, v79
	ds_write2_b32 v4, v2, v3 offset1:1
	v_pk_mul_f32 v[2:3], v[26:27], v[86:87] op_sel_hi:[1,0]
	v_add_u32_e32 v4, 0x14a0, v79
	s_mul_hi_i32 s4, s26, 0x2e8ba2e9
	ds_write2_b32 v4, v2, v3 offset1:1
	v_pk_mul_f32 v[2:3], v[28:29], v[86:87] op_sel_hi:[1,0]
	v_add_u32_e32 v4, 0x14a8, v79
	s_lshr_b32 s5, s4, 31
	s_ashr_i32 s4, s4, 6
	ds_write2_b32 v4, v2, v3 offset1:1
	v_pk_mul_f32 v[2:3], v[30:31], v[88:89] op_sel_hi:[1,0]
	v_add_u32_e32 v4, 0x18c0, v79
	s_add_i32 s6, s4, s5
	ds_write2_b32 v4, v2, v3 offset1:1
	v_pk_mul_f32 v[2:3], v[32:33], v[88:89] op_sel_hi:[1,0]
	v_add_u32_e32 v4, 0x18c8, v79
	s_lshl_b32 s4, s6, 6
	ds_write2_b32 v4, v2, v3 offset1:1
	s_waitcnt vmcnt(0)
	v_pk_mul_f32 v[2:3], v[38:39], v[90:91] op_sel_hi:[1,0]
	v_add_u32_e32 v4, 0x1ce0, v79
	ds_write2_b32 v4, v2, v3 offset1:1
	v_pk_mul_f32 v[2:3], v[40:41], v[90:91] op_sel_hi:[1,0]
	v_add_u32_e32 v4, 0x1ce8, v79
	s_ashr_i32 s5, s4, 31
	ds_write2_b32 v4, v2, v3 offset1:1
	v_lshl_add_u64 v[24:25], s[4:5], 1, v[82:83]
	s_mul_i32 s4, s6, 0xffffd400
	s_waitcnt lgkmcnt(0)
	s_add_i32 s4, s4, s28
	ds_read2_b32 v[6:7], v77 offset0:33 offset1:41
	ds_read2_b32 v[8:9], v77 offset1:8
	ds_read2_b32 v[10:11], v77 offset0:66 offset1:74
	ds_read2_b32 v[12:13], v77 offset0:99 offset1:107
	ds_read2_b32 v[14:15], v77 offset0:132 offset1:140
	ds_read2_b32 v[16:17], v77 offset0:165 offset1:173
	ds_read2_b32 v[18:19], v77 offset0:198 offset1:206
	ds_read2_b32 v[20:21], v77 offset0:231 offset1:239
	v_add_u32_e32 v28, s4, v87
	s_waitcnt lgkmcnt(6)
	v_cvt_pk_bf16_f32 v2, v8, v6
	v_add_u32_e32 v6, 0xffffea00, v28
	v_cmp_lt_i32_e32 vcc, s34, v28
	s_waitcnt lgkmcnt(4)
	v_cvt_pk_bf16_f32 v3, v10, v12
	s_waitcnt lgkmcnt(2)
	v_cvt_pk_bf16_f32 v4, v14, v16
	v_cndmask_b32_e32 v6, v28, v6, vcc
	v_lshlrev_b32_e32 v8, 1, v6
	v_and_b32_e32 v8, 0xffffff00, v8
	v_cndmask_b32_e32 v10, 0, v85, vcc
	v_and_b32_e32 v6, 0x67, v6
	v_or3_b32 v26, v6, v10, v8
	v_ashrrev_i32_e32 v27, 31, v26
	v_lshlrev_b64 v[26:27], 12, v[26:27]
	s_waitcnt lgkmcnt(0)
	v_cvt_pk_bf16_f32 v5, v18, v20
	v_lshl_add_u64 v[26:27], v[24:25], 0, v[26:27]
	v_add_u32_e32 v6, 8, v28
	global_store_dwordx4 v[26:27], v[2:5], off
	v_cmp_lt_i32_e32 vcc, s34, v6
	v_mov_b64_e32 v[30:31], v[62:63]
	v_cvt_pk_bf16_f32 v2, v9, v7
	v_add_u32_e32 v7, 0xffffea08, v28
	v_cndmask_b32_e32 v6, v6, v7, vcc
	v_lshlrev_b32_e32 v7, 1, v6
	v_and_b32_e32 v7, 0xffffff00, v7
	v_cndmask_b32_e32 v8, 0, v85, vcc
	v_and_b32_e32 v6, 0x6f, v6
	v_or3_b32 v6, v6, v8, v7
	v_ashrrev_i32_e32 v7, 31, v6
	v_lshlrev_b64 v[6:7], 12, v[6:7]
	v_cvt_pk_bf16_f32 v3, v11, v13
	v_cvt_pk_bf16_f32 v4, v15, v17
	v_cvt_pk_bf16_f32 v5, v19, v21
	v_lshl_add_u64 v[6:7], v[24:25], 0, v[6:7]
	ds_read2_b32 v[8:9], v77 offset0:16 offset1:24
	ds_read2_b32 v[10:11], v77 offset0:49 offset1:57
	ds_read2_b32 v[12:13], v77 offset0:82 offset1:90
	ds_read2_b32 v[14:15], v77 offset0:115 offset1:123
	ds_read2_b32 v[16:17], v77 offset0:148 offset1:156
	ds_read2_b32 v[18:19], v77 offset0:181 offset1:189
	ds_read2_b32 v[20:21], v77 offset0:214 offset1:222
	ds_read2_b32 v[26:27], v77 offset0:247 offset1:255
	global_store_dwordx4 v[6:7], v[2:5], off
	v_add_u32_e32 v6, 16, v28
	v_add_u32_e32 v7, 0xffffea10, v28
	v_cmp_lt_i32_e32 vcc, s34, v6
	s_waitcnt lgkmcnt(6)
	v_cvt_pk_bf16_f32 v2, v8, v10
	s_waitcnt lgkmcnt(4)
	v_cvt_pk_bf16_f32 v3, v12, v14
	v_cndmask_b32_e32 v6, v6, v7, vcc
	v_lshlrev_b32_e32 v7, 1, v6
	v_and_b32_e32 v7, 0xffffff00, v7
	v_cndmask_b32_e32 v8, 0, v85, vcc
	v_and_b32_e32 v6, 0x77, v6
	v_or3_b32 v6, v6, v8, v7
	v_ashrrev_i32_e32 v7, 31, v6
	v_lshlrev_b64 v[6:7], 12, v[6:7]
	s_waitcnt lgkmcnt(2)
	v_cvt_pk_bf16_f32 v4, v16, v18
	s_waitcnt lgkmcnt(0)
	v_cvt_pk_bf16_f32 v5, v20, v26
	v_lshl_add_u64 v[6:7], v[24:25], 0, v[6:7]
	global_store_dwordx4 v[6:7], v[2:5], off
	v_mov_b64_e32 v[38:39], v[66:67]
	v_add_u32_e32 v87, s29, v87
	v_add_u32_e32 v2, 24, v28
	v_add_u32_e32 v3, 0xffffea18, v28
	v_cmp_lt_i32_e32 vcc, s34, v2
	v_cvt_pk_bf16_f32 v5, v21, v27
	v_mov_b64_e32 v[26:27], v[58:59]
	v_cndmask_b32_e32 v2, v2, v3, vcc
	v_lshlrev_b32_e32 v3, 1, v2
	v_and_b32_e32 v3, 0xffffff00, v3
	v_cndmask_b32_e32 v4, 0, v85, vcc
	v_and_b32_e32 v2, 0x7f, v2
	v_or3_b32 v6, v2, v4, v3
	v_ashrrev_i32_e32 v7, 31, v6
	v_lshlrev_b64 v[6:7], 12, v[6:7]
	v_cvt_pk_bf16_f32 v2, v9, v11
	v_cvt_pk_bf16_f32 v3, v13, v15
	v_cvt_pk_bf16_f32 v4, v17, v19
	v_lshl_add_u64 v[6:7], v[24:25], 0, v[6:7]
	global_store_dwordx4 v[6:7], v[2:5], off sc0 sc1
	s_waitcnt lgkmcnt(0)
	v_mov_b64_e32 v[6:7], v[42:43]
	v_mov_b64_e32 v[10:11], v[46:47]
	v_mov_b64_e32 v[2:3], v[34:35]
	v_mov_b64_e32 v[14:15], v[50:51]
	v_mov_b64_e32 v[18:19], v[54:55]
	s_add_i32 s35, s35, s29
	v_add_u32_e32 v73, s29, v73
	s_andn2_b64 vcc, exec, s[18:19]
	s_mov_b32 s26, s36
	v_mov_b64_e32 v[4:5], v[36:37]
	v_mov_b64_e32 v[8:9], v[44:45]
	v_mov_b64_e32 v[12:13], v[48:49]
	v_mov_b64_e32 v[16:17], v[52:53]
	v_mov_b64_e32 v[20:21], v[56:57]
	v_mov_b64_e32 v[28:29], v[60:61]
	v_mov_b64_e32 v[32:33], v[64:65]
	v_mov_b64_e32 v[40:41], v[68:69]
	v_mov_b32_e32 v72, v91
	v_mov_b32_e32 v74, v96
	v_mov_b32_e32 v76, v97
	v_mov_b32_e32 v78, v98
	v_mov_b32_e32 v84, v99
	v_mov_b32_e32 v86, v100
	v_mov_b32_e32 v88, v101
	v_mov_b32_e32 v90, v23
	s_cbranch_vccz .LBB0_422

; #define LAS __attribute__((address_space(3)))
; __device__ __forceinline__ unsigned cvtpk(float lo, float hi) { f32x2 v = {lo, hi}; bf16x2_t b = __builtin_convertvector(v, bf16x2_t); return __builtin_bit_cast(unsigned, b); }
; __device__ __forceinline__ void witem_store(const WItem& w, int K, bf16_t* WT, int kvperm, LAS float* scr, int item, int nblk, int lane) {
;     const int kb = item / nblk, nb = item % nblk, k0 = 64 * kb, n0 = 32 * nb;
;     const int col = 4 * (lane & 7), rr = lane >> 3;
; #pragma unroll
;     for (int i = 0; i < 8; ++i) { LAS float* d = scr + (8 * i + rr) * 33 + col; const float g = w.g[i]; d[0] = w.v[i].x * g; d[1] = w.v[i].y * g; d[2] = w.v[i].z * g; d[3] = w.v[i].w * g; }
;     asm volatile("s_waitcnt lgkmcnt(0)" ::: "memory");
;     const int c = lane & 7;
; #pragma unroll
;     for (int j = 0; j < 4; ++j) { const int n = (lane >> 3) + 8 * j; const LAS float* s = scr + (8 * c) * 33 + n;
;         u32x4 o; o.x = cvtpk(s[0 * 33], s[1 * 33]); o.y = cvtpk(s[2 * 33], s[3 * 33]); o.z = cvtpk(s[4 * 33], s[5 * 33]); o.w = cvtpk(s[6 * 33], s[7 * 33]);
;         int nr = n0 + n; if (kvperm == 1) { const int hh = nr >> 8, ww = nr & 255; nr = (ww < 128) ? hh * 128 + ww : 2048 + hh * 128 + (ww - 128); }
;         else if (kvperm == 2) { const int isv = nr >= 5632, f = isv ? nr - 5632 : nr; nr = (f >> 7) * 256 + isv * 128 + (f & 127); }
;         *(u32x4*)(WT + (size_t)nr * K + k0 + 8 * c) = o; }
.LBB0_515:
	v_pk_mul_f32 v[4:5], v[18:19], v[76:77] op_sel_hi:[1,0]
	ds_write2_b32 v81, v4, v5 offset1:1
	v_pk_mul_f32 v[4:5], v[20:21], v[76:77] op_sel_hi:[1,0]
	ds_write2_b32 v81, v4, v5 offset0:2 offset1:3
	v_pk_mul_f32 v[4:5], v[6:7], v[78:79] op_sel_hi:[1,0]
	v_add_u32_e32 v6, 0x420, v81
	ds_write2_b32 v6, v4, v5 offset1:1
	v_pk_mul_f32 v[4:5], v[8:9], v[78:79] op_sel_hi:[1,0]
	v_add_u32_e32 v6, 0x428, v81
	ds_write2_b32 v6, v4, v5 offset1:1
	v_pk_mul_f32 v[4:5], v[26:27], v[80:81] op_sel_hi:[1,0]
	v_add_u32_e32 v6, 0x840, v81
	ds_write2_b32 v6, v4, v5 offset1:1
	v_pk_mul_f32 v[4:5], v[28:29], v[80:81] op_sel_hi:[1,0]
	v_add_u32_e32 v6, 0x848, v81
	ds_write2_b32 v6, v4, v5 offset1:1
	v_pk_mul_f32 v[4:5], v[22:23], v[82:83] op_sel_hi:[1,0]
	v_add_u32_e32 v6, 0xc60, v81
	ds_write2_b32 v6, v4, v5 offset1:1
	v_pk_mul_f32 v[4:5], v[24:25], v[82:83] op_sel_hi:[1,0]
	v_add_u32_e32 v6, 0xc68, v81
	ds_write2_b32 v6, v4, v5 offset1:1
	v_pk_mul_f32 v[4:5], v[42:43], v[84:85] op_sel_hi:[1,0]
	v_add_u32_e32 v6, 0x1080, v81
	ds_write2_b32 v6, v4, v5 offset1:1
	v_pk_mul_f32 v[4:5], v[44:45], v[84:85] op_sel_hi:[1,0]
	v_add_u32_e32 v6, 0x1088, v81
	ds_write2_b32 v6, v4, v5 offset1:1
	s_waitcnt vmcnt(7)
	v_pk_mul_f32 v[4:5], v[34:35], v[86:87] op_sel_hi:[1,0]
	v_add_u32_e32 v6, 0x14a0, v81
	s_mul_hi_i32 s12, s19, 0x2e8ba2e9
	ds_write2_b32 v6, v4, v5 offset1:1
	v_pk_mul_f32 v[4:5], v[36:37], v[86:87] op_sel_hi:[1,0]
	v_add_u32_e32 v6, 0x14a8, v81
	s_lshr_b32 s13, s12, 31
	s_ashr_i32 s12, s12, 6
	ds_write2_b32 v6, v4, v5 offset1:1
	s_waitcnt vmcnt(6)
	v_pk_mul_f32 v[4:5], v[54:55], v[88:89] op_sel_hi:[1,0]
	v_add_u32_e32 v6, 0x18c0, v81
	s_add_i32 s19, s12, s13
	ds_write2_b32 v6, v4, v5 offset1:1
	v_pk_mul_f32 v[4:5], v[56:57], v[88:89] op_sel_hi:[1,0]
	v_add_u32_e32 v6, 0x18c8, v81
	s_lshl_b32 s12, s19, 6
	ds_write2_b32 v6, v4, v5 offset1:1
	s_waitcnt vmcnt(5)
	v_pk_mul_f32 v[4:5], v[46:47], v[90:91] op_sel_hi:[1,0]
	v_add_u32_e32 v6, 0x1ce0, v81
	ds_write2_b32 v6, v4, v5 offset1:1
	v_pk_mul_f32 v[4:5], v[48:49], v[90:91] op_sel_hi:[1,0]
	v_add_u32_e32 v6, 0x1ce8, v81
	s_ashr_i32 s13, s12, 31
	ds_write2_b32 v6, v4, v5 offset1:1
	v_lshl_add_u64 v[36:37], s[12:13], 1, v[74:75]
	s_mul_i32 s12, s19, 0xffffd400
	s_waitcnt lgkmcnt(0)
	s_add_i32 s12, s12, s2
	ds_read2_b32 v[8:9], v79 offset0:33 offset1:41
	ds_read2_b32 v[18:19], v79 offset1:8
	ds_read2_b32 v[20:21], v79 offset0:66 offset1:74
	ds_read2_b32 v[22:23], v79 offset0:99 offset1:107
	ds_read2_b32 v[24:25], v79 offset0:132 offset1:140
	ds_read2_b32 v[26:27], v79 offset0:165 offset1:173
	ds_read2_b32 v[28:29], v79 offset0:198 offset1:206
	ds_read2_b32 v[34:35], v79 offset0:231 offset1:239
	v_add_u32_e32 v44, s12, v85
	s_waitcnt lgkmcnt(6)
	v_cvt_pk_bf16_f32 v4, v18, v8
	v_add_u32_e32 v8, 0xffffea00, v44
	v_cmp_lt_i32_e32 vcc, s18, v44
	s_waitcnt lgkmcnt(4)
	v_cvt_pk_bf16_f32 v5, v20, v22
	s_waitcnt lgkmcnt(2)
	v_cvt_pk_bf16_f32 v6, v24, v26
	v_cndmask_b32_e32 v8, v44, v8, vcc
	v_lshlrev_b32_e32 v18, 1, v8
	v_and_b32_e32 v18, 0xffffff00, v18
	v_cndmask_b32_e32 v20, 0, v83, vcc
	v_and_b32_e32 v8, 0x67, v8
	v_or3_b32 v42, v8, v20, v18
	v_ashrrev_i32_e32 v43, 31, v42
	v_lshlrev_b64 v[42:43], 12, v[42:43]
	s_waitcnt lgkmcnt(0)
	v_cvt_pk_bf16_f32 v7, v28, v34
	v_lshl_add_u64 v[42:43], v[36:37], 0, v[42:43]
	v_add_u32_e32 v8, 8, v44
	global_store_dwordx4 v[42:43], v[4:7], off
	v_cmp_lt_i32_e32 vcc, s18, v8
	s_waitcnt vmcnt(3)
	v_mov_b64_e32 v[54:55], v[62:63]
	v_cvt_pk_bf16_f32 v4, v19, v9
	v_add_u32_e32 v9, 0xffffea08, v44
	v_cndmask_b32_e32 v8, v8, v9, vcc
	v_lshlrev_b32_e32 v9, 1, v8
	v_and_b32_e32 v9, 0xffffff00, v9
	v_cndmask_b32_e32 v18, 0, v83, vcc
	v_and_b32_e32 v8, 0x6f, v8
	v_or3_b32 v8, v8, v18, v9
	v_ashrrev_i32_e32 v9, 31, v8
	v_lshlrev_b64 v[8:9], 12, v[8:9]
	v_cvt_pk_bf16_f32 v5, v21, v23
	v_cvt_pk_bf16_f32 v6, v25, v27
	v_cvt_pk_bf16_f32 v7, v29, v35
	v_lshl_add_u64 v[8:9], v[36:37], 0, v[8:9]
	ds_read2_b32 v[18:19], v79 offset0:16 offset1:24
	ds_read2_b32 v[20:21], v79 offset0:49 offset1:57
	ds_read2_b32 v[22:23], v79 offset0:82 offset1:90
	ds_read2_b32 v[24:25], v79 offset0:115 offset1:123
	ds_read2_b32 v[26:27], v79 offset0:148 offset1:156
	ds_read2_b32 v[28:29], v79 offset0:181 offset1:189
	ds_read2_b32 v[34:35], v79 offset0:214 offset1:222
	ds_read2_b32 v[42:43], v79 offset0:247 offset1:255
	global_store_dwordx4 v[8:9], v[4:7], off
	v_add_u32_e32 v8, 16, v44
	v_add_u32_e32 v9, 0xffffea10, v44
	v_cmp_lt_i32_e32 vcc, s18, v8
	s_waitcnt lgkmcnt(6)
	v_cvt_pk_bf16_f32 v4, v18, v20
	s_waitcnt lgkmcnt(4)
	v_cvt_pk_bf16_f32 v5, v22, v24
	v_cndmask_b32_e32 v8, v8, v9, vcc
	v_lshlrev_b32_e32 v9, 1, v8
	v_and_b32_e32 v9, 0xffffff00, v9
	v_cndmask_b32_e32 v18, 0, v83, vcc
	v_and_b32_e32 v8, 0x77, v8
	v_or3_b32 v8, v8, v18, v9
	v_ashrrev_i32_e32 v9, 31, v8
	v_lshlrev_b64 v[8:9], 12, v[8:9]
	s_waitcnt lgkmcnt(2)
	v_cvt_pk_bf16_f32 v6, v26, v28
	s_waitcnt lgkmcnt(0)
	v_cvt_pk_bf16_f32 v7, v34, v42
	v_lshl_add_u64 v[8:9], v[36:37], 0, v[8:9]
	global_store_dwordx4 v[8:9], v[4:7], off
	s_waitcnt vmcnt(4)
	v_mov_b64_e32 v[46:47], v[66:67]
	v_add_u32_e32 v85, s14, v85
	v_add_u32_e32 v4, 24, v44
	v_add_u32_e32 v5, 0xffffea18, v44
	v_cmp_lt_i32_e32 vcc, s18, v4
	v_cvt_pk_bf16_f32 v7, v35, v43
	v_mov_b64_e32 v[42:43], v[50:51]
	v_cndmask_b32_e32 v4, v4, v5, vcc
	v_lshlrev_b32_e32 v5, 1, v4
	v_and_b32_e32 v5, 0xffffff00, v5
	v_cndmask_b32_e32 v6, 0, v83, vcc
	v_and_b32_e32 v4, 0x7f, v4
	v_or3_b32 v8, v4, v6, v5
	v_ashrrev_i32_e32 v9, 31, v8
	v_lshlrev_b64 v[8:9], 12, v[8:9]
	v_cvt_pk_bf16_f32 v4, v19, v21
	v_cvt_pk_bf16_f32 v5, v23, v25
	v_cvt_pk_bf16_f32 v6, v27, v29
	v_lshl_add_u64 v[8:9], v[36:37], 0, v[8:9]
	global_store_dwordx4 v[8:9], v[4:7], off sc0 sc1
	s_waitcnt lgkmcnt(0)
	v_mov_b64_e32 v[20:21], v[16:17]
	v_mov_b64_e32 v[26:27], v[30:31]
	v_mov_b64_e32 v[6:7], v[10:11]
	v_mov_b64_e32 v[22:23], v[38:39]
	v_mov_b64_e32 v[34:35], v[58:59]
	s_add_i32 s20, s20, s14
	v_add_u32_e32 v77, s14, v77
	s_andn2_b64 vcc, exec, s[6:7]
	s_mov_b32 s19, s21
	v_mov_b64_e32 v[18:19], v[14:15]
	v_mov_b64_e32 v[8:9], v[12:13]
	v_mov_b64_e32 v[28:29], v[32:33]
	v_mov_b64_e32 v[24:25], v[40:41]
	v_mov_b64_e32 v[44:45], v[52:53]
	v_mov_b64_e32 v[36:37], v[60:61]
	v_mov_b64_e32 v[56:57], v[64:65]
	v_mov_b64_e32 v[48:49], v[68:69]
	v_mov_b32_e32 v76, v87
	v_mov_b32_e32 v78, v89
	v_mov_b32_e32 v80, v91
	v_mov_b32_e32 v82, v93
	v_mov_b32_e32 v84, v98
	v_mov_b32_e32 v86, v99
	v_mov_b32_e32 v88, v100
	s_waitcnt vmcnt(4)
	v_mov_b32_e32 v90, v3
	s_cbranch_vccz .LBB0_533

; #define LAS __attribute__((address_space(3)))
; __device__ __forceinline__ unsigned cvtpk(float lo, float hi) { f32x2 v = {lo, hi}; bf16x2_t b = __builtin_convertvector(v, bf16x2_t); return __builtin_bit_cast(unsigned, b); }
; __device__ __forceinline__ void witem_store(const WItem& w, int K, bf16_t* WT, int kvperm, LAS float* scr, int item, int nblk, int lane) {
;     ...
;     for (int i = 0; i < 8; ++i) { LAS float* d = scr + (8 * i + rr) * 33 + col; const float g = w.g[i]; d[0] = w.v[i].x * g; d[1] = w.v[i].y * g; d[2] = w.v[i].z * g; d[3] = w.v[i].w * g; }
;     asm volatile("s_waitcnt lgkmcnt(0)" ::: "memory");
;     const int c = lane & 7;
; #pragma unroll
;     for (int j = 0; j < 4; ++j) { const int n = (lane >> 3) + 8 * j; const LAS float* s = scr + (8 * c) * 33 + n;
;         u32x4 o; o.x = cvtpk(s[0 * 33], s[1 * 33]); o.y = cvtpk(s[2 * 33], s[3 * 33]); o.z = cvtpk(s[4 * 33], s[5 * 33]); o.w = cvtpk(s[6 * 33], s[7 * 33]);
;         int nr = n0 + n; if (kvperm == 1) { const int hh = nr >> 8, ww = nr & 255; nr = (ww < 128) ? hh * 128 + ww : 2048 + hh * 128 + (ww - 128); }
;         else if (kvperm == 2) { const int isv = nr >= 5632, f = isv ? nr - 5632 : nr; nr = (f >> 7) * 256 + isv * 128 + (f & 127); }
;         *(u32x4*)(WT + (size_t)nr * K + k0 + 8 * c) = o; }
;     ...
;     while (it < i1) {
;         cur = nxt;
;         const int nit = it + NGW;
;         if (nit < i1) witem_load(nxt, W, N, gk, nit, nblk, lane);
;         witem_store(cur, K, WT, kvperm, scr, it, nblk, lane);
;         it = nit;
;     }
.LBB0_737:
	v_pk_mul_f32 v[2:3], v[16:17], v[72:73] op_sel_hi:[1,0]
	ds_write2_b32 v79, v2, v3 offset1:1
	v_pk_mul_f32 v[2:3], v[18:19], v[72:73] op_sel_hi:[1,0]
	ds_write2_b32 v79, v2, v3 offset0:2 offset1:3
	v_pk_mul_f32 v[2:3], v[4:5], v[74:75] op_sel_hi:[1,0]
	v_add_u32_e32 v4, 0x420, v79
	ds_write2_b32 v4, v2, v3 offset1:1
	v_pk_mul_f32 v[2:3], v[6:7], v[74:75] op_sel_hi:[1,0]
	v_add_u32_e32 v4, 0x428, v79
	ds_write2_b32 v4, v2, v3 offset1:1
	v_pk_mul_f32 v[2:3], v[24:25], v[76:77] op_sel_hi:[1,0]
	v_add_u32_e32 v4, 0x840, v79
	ds_write2_b32 v4, v2, v3 offset1:1
	v_pk_mul_f32 v[2:3], v[26:27], v[76:77] op_sel_hi:[1,0]
	v_add_u32_e32 v4, 0x848, v79
	ds_write2_b32 v4, v2, v3 offset1:1
	v_pk_mul_f32 v[2:3], v[20:21], v[78:79] op_sel_hi:[1,0]
	v_add_u32_e32 v4, 0xc60, v79
	ds_write2_b32 v4, v2, v3 offset1:1
	v_pk_mul_f32 v[2:3], v[22:23], v[78:79] op_sel_hi:[1,0]
	v_add_u32_e32 v4, 0xc68, v79
	ds_write2_b32 v4, v2, v3 offset1:1
	v_pk_mul_f32 v[2:3], v[36:37], v[80:81] op_sel_hi:[1,0]
	v_add_u32_e32 v4, 0x1080, v79
	ds_write2_b32 v4, v2, v3 offset1:1
	v_pk_mul_f32 v[2:3], v[38:39], v[80:81] op_sel_hi:[1,0]
	v_add_u32_e32 v4, 0x1088, v79
	ds_write2_b32 v4, v2, v3 offset1:1
	v_pk_mul_f32 v[2:3], v[32:33], v[82:83] op_sel_hi:[1,0]
	v_add_u32_e32 v4, 0x14a0, v79
	s_mul_hi_i32 s6, s11, 0x2e8ba2e9
	ds_write2_b32 v4, v2, v3 offset1:1
	v_pk_mul_f32 v[2:3], v[34:35], v[82:83] op_sel_hi:[1,0]
	v_add_u32_e32 v4, 0x14a8, v79
	s_lshr_b32 s7, s6, 31
	s_ashr_i32 s6, s6, 6
	ds_write2_b32 v4, v2, v3 offset1:1
	s_waitcnt vmcnt(7)
	v_pk_mul_f32 v[2:3], v[52:53], v[84:85] op_sel_hi:[1,0]
	v_add_u32_e32 v4, 0x18c0, v79
	s_add_i32 s11, s6, s7
	ds_write2_b32 v4, v2, v3 offset1:1
	v_pk_mul_f32 v[2:3], v[54:55], v[84:85] op_sel_hi:[1,0]
	v_add_u32_e32 v4, 0x18c8, v79
	s_lshl_b32 s6, s11, 6
	ds_write2_b32 v4, v2, v3 offset1:1
	s_waitcnt vmcnt(6)
	v_pk_mul_f32 v[2:3], v[44:45], v[86:87] op_sel_hi:[1,0]
	v_add_u32_e32 v4, 0x1ce0, v79
	ds_write2_b32 v4, v2, v3 offset1:1
	v_pk_mul_f32 v[2:3], v[46:47], v[86:87] op_sel_hi:[1,0]
	v_add_u32_e32 v4, 0x1ce8, v79
	s_ashr_i32 s7, s6, 31
	ds_write2_b32 v4, v2, v3 offset1:1
	v_lshl_add_u64 v[34:35], s[6:7], 1, v[70:71]
	s_mul_i32 s6, s11, 0xffffd400
	s_waitcnt lgkmcnt(0)
	s_add_i32 s6, s6, s8
	ds_read2_b32 v[6:7], v75 offset0:33 offset1:41
	ds_read2_b32 v[16:17], v75 offset1:8
	ds_read2_b32 v[18:19], v75 offset0:66 offset1:74
	ds_read2_b32 v[20:21], v75 offset0:99 offset1:107
	ds_read2_b32 v[22:23], v75 offset0:132 offset1:140
	ds_read2_b32 v[24:25], v75 offset0:165 offset1:173
	ds_read2_b32 v[26:27], v75 offset0:198 offset1:206
	ds_read2_b32 v[32:33], v75 offset0:231 offset1:239
	v_add_u32_e32 v38, s6, v83
	s_waitcnt lgkmcnt(6)
	v_cvt_pk_bf16_f32 v2, v16, v6
	v_add_u32_e32 v6, 0xffffea00, v38
	v_cmp_lt_i32_e32 vcc, s14, v38
	s_waitcnt lgkmcnt(4)
	v_cvt_pk_bf16_f32 v3, v18, v20
	s_waitcnt lgkmcnt(2)
	v_cvt_pk_bf16_f32 v4, v22, v24
	v_cndmask_b32_e32 v6, v38, v6, vcc
	v_lshlrev_b32_e32 v16, 1, v6
	v_and_b32_e32 v16, 0xffffff00, v16
	v_cndmask_b32_e32 v18, 0, v81, vcc
	v_and_b32_e32 v6, 0x67, v6
	v_or3_b32 v36, v6, v18, v16
	v_ashrrev_i32_e32 v37, 31, v36
	v_lshlrev_b64 v[36:37], 12, v[36:37]
	s_waitcnt lgkmcnt(0)
	v_cvt_pk_bf16_f32 v5, v26, v32
	v_lshl_add_u64 v[36:37], v[34:35], 0, v[36:37]
	v_add_u32_e32 v6, 8, v38
	global_store_dwordx4 v[36:37], v[2:5], off
	v_cmp_lt_i32_e32 vcc, s14, v6
	s_waitcnt vmcnt(3)
	v_mov_b64_e32 v[52:53], v[60:61]
	v_cvt_pk_bf16_f32 v2, v17, v7
	v_add_u32_e32 v7, 0xffffea08, v38
	v_cndmask_b32_e32 v6, v6, v7, vcc
	v_lshlrev_b32_e32 v7, 1, v6
	v_and_b32_e32 v7, 0xffffff00, v7
	v_cndmask_b32_e32 v16, 0, v81, vcc
	v_and_b32_e32 v6, 0x6f, v6
	v_or3_b32 v6, v6, v16, v7
	v_ashrrev_i32_e32 v7, 31, v6
	v_lshlrev_b64 v[6:7], 12, v[6:7]
	v_cvt_pk_bf16_f32 v3, v19, v21
	v_cvt_pk_bf16_f32 v4, v23, v25
	v_cvt_pk_bf16_f32 v5, v27, v33
	v_lshl_add_u64 v[6:7], v[34:35], 0, v[6:7]
	ds_read2_b32 v[16:17], v75 offset0:16 offset1:24
	ds_read2_b32 v[18:19], v75 offset0:49 offset1:57
	ds_read2_b32 v[20:21], v75 offset0:82 offset1:90
	ds_read2_b32 v[22:23], v75 offset0:115 offset1:123
	ds_read2_b32 v[24:25], v75 offset0:148 offset1:156
	ds_read2_b32 v[26:27], v75 offset0:181 offset1:189
	ds_read2_b32 v[32:33], v75 offset0:214 offset1:222
	ds_read2_b32 v[36:37], v75 offset0:247 offset1:255
	global_store_dwordx4 v[6:7], v[2:5], off
	v_add_u32_e32 v6, 16, v38
	v_add_u32_e32 v7, 0xffffea10, v38
	v_cmp_lt_i32_e32 vcc, s14, v6
	s_waitcnt lgkmcnt(6)
	v_cvt_pk_bf16_f32 v2, v16, v18
	s_waitcnt lgkmcnt(4)
	v_cvt_pk_bf16_f32 v3, v20, v22
	v_cndmask_b32_e32 v6, v6, v7, vcc
	v_lshlrev_b32_e32 v7, 1, v6
	v_and_b32_e32 v7, 0xffffff00, v7
	v_cndmask_b32_e32 v16, 0, v81, vcc
	v_and_b32_e32 v6, 0x77, v6
	v_or3_b32 v6, v6, v16, v7
	v_ashrrev_i32_e32 v7, 31, v6
	v_lshlrev_b64 v[6:7], 12, v[6:7]
	s_waitcnt lgkmcnt(2)
	v_cvt_pk_bf16_f32 v4, v24, v26
	s_waitcnt lgkmcnt(0)
	v_cvt_pk_bf16_f32 v5, v32, v36
	v_lshl_add_u64 v[6:7], v[34:35], 0, v[6:7]
	global_store_dwordx4 v[6:7], v[2:5], off
	s_waitcnt vmcnt(4)
	v_mov_b64_e32 v[44:45], v[64:65]
	v_add_u32_e32 v83, s9, v83
	v_add_u32_e32 v2, 24, v38
	v_add_u32_e32 v3, 0xffffea18, v38
	v_cmp_lt_i32_e32 vcc, s14, v2
	v_cvt_pk_bf16_f32 v5, v33, v37
	v_mov_b64_e32 v[36:37], v[48:49]
	v_cndmask_b32_e32 v2, v2, v3, vcc
	v_lshlrev_b32_e32 v3, 1, v2
	v_and_b32_e32 v3, 0xffffff00, v3
	v_cndmask_b32_e32 v4, 0, v81, vcc
	v_and_b32_e32 v2, 0x7f, v2
	v_or3_b32 v6, v2, v4, v3
	v_ashrrev_i32_e32 v7, 31, v6
	v_lshlrev_b64 v[6:7], 12, v[6:7]
	v_cvt_pk_bf16_f32 v2, v17, v19
	v_cvt_pk_bf16_f32 v3, v21, v23
	v_cvt_pk_bf16_f32 v4, v25, v27
	v_lshl_add_u64 v[6:7], v[34:35], 0, v[6:7]
	global_store_dwordx4 v[6:7], v[2:5], off sc0 sc1
	s_waitcnt lgkmcnt(0)
	v_mov_b64_e32 v[18:19], v[14:15]
	v_mov_b64_e32 v[24:25], v[28:29]
	v_mov_b64_e32 v[4:5], v[8:9]
	v_mov_b64_e32 v[20:21], v[40:41]
	v_mov_b64_e32 v[32:33], v[56:57]
	s_add_i32 s15, s15, s9
	v_add_u32_e32 v73, s9, v73
	s_andn2_b64 vcc, exec, s[0:1]
	s_mov_b32 s11, s16
	v_mov_b64_e32 v[16:17], v[12:13]
	v_mov_b64_e32 v[6:7], v[10:11]
	v_mov_b64_e32 v[26:27], v[30:31]
	v_mov_b64_e32 v[22:23], v[42:43]
	v_mov_b64_e32 v[38:39], v[50:51]
	v_mov_b64_e32 v[34:35], v[58:59]
	v_mov_b64_e32 v[54:55], v[62:63]
	v_mov_b64_e32 v[46:47], v[66:67]
	v_mov_b32_e32 v72, v85
	v_mov_b32_e32 v74, v87
	v_mov_b32_e32 v76, v89
	v_mov_b32_e32 v78, v94
	v_mov_b32_e32 v80, v95
	v_mov_b32_e32 v82, v96
	v_mov_b32_e32 v84, v97
	s_waitcnt vmcnt(4)
	v_mov_b32_e32 v86, v1
	s_cbranch_vccz .LBB0_755

; #define LAS __attribute__((address_space(3)))
; __device__ __forceinline__ unsigned cvtpk(float lo, float hi) { f32x2 v = {lo, hi}; bf16x2_t b = __builtin_convertvector(v, bf16x2_t); return __builtin_bit_cast(unsigned, b); }
; __device__ __forceinline__ void witem_store(const WItem& w, int K, bf16_t* WT, int kvperm, LAS float* scr, int item, int nblk, int lane) {
;     ...
;     for (int i = 0; i < 8; ++i) { LAS float* d = scr + (8 * i + rr) * 33 + col; const float g = w.g[i]; d[0] = w.v[i].x * g; d[1] = w.v[i].y * g; d[2] = w.v[i].z * g; d[3] = w.v[i].w * g; }
;     asm volatile("s_waitcnt lgkmcnt(0)" ::: "memory");
;     const int c = lane & 7;
; #pragma unroll
;     for (int j = 0; j < 4; ++j) { const int n = (lane >> 3) + 8 * j; const LAS float* s = scr + (8 * c) * 33 + n;
;         u32x4 o; o.x = cvtpk(s[0 * 33], s[1 * 33]); o.y = cvtpk(s[2 * 33], s[3 * 33]); o.z = cvtpk(s[4 * 33], s[5 * 33]); o.w = cvtpk(s[6 * 33], s[7 * 33]);
;         int nr = n0 + n; if (kvperm == 1) { const int hh = nr >> 8, ww = nr & 255; nr = (ww < 128) ? hh * 128 + ww : 2048 + hh * 128 + (ww - 128); }
;         else if (kvperm == 2) { const int isv = nr >= 5632, f = isv ? nr - 5632 : nr; nr = (f >> 7) * 256 + isv * 128 + (f & 127); }
;         *(u32x4*)(WT + (size_t)nr * K + k0 + 8 * c) = o; }
;     ...
;     while (it < i1) {
;         cur = nxt;
;         const int nit = it + NGW;
;         if (nit < i1) witem_load(nxt, W, N, gk, nit, nblk, lane);
;         witem_store(cur, K, WT, kvperm, scr, it, nblk, lane);
;         it = nit;
;     }
.LBB0_1205:
	v_pk_mul_f32 v[2:3], v[12:13], v[72:73] op_sel_hi:[1,0]
	ds_write2_b32 v79, v2, v3 offset1:1
	v_pk_mul_f32 v[2:3], v[14:15], v[72:73] op_sel_hi:[1,0]
	ds_write2_b32 v79, v2, v3 offset0:2 offset1:3
	v_pk_mul_f32 v[2:3], v[4:5], v[74:75] op_sel_hi:[1,0]
	v_add_u32_e32 v4, 0x420, v79
	ds_write2_b32 v4, v2, v3 offset1:1
	v_pk_mul_f32 v[2:3], v[6:7], v[74:75] op_sel_hi:[1,0]
	v_add_u32_e32 v4, 0x428, v79
	ds_write2_b32 v4, v2, v3 offset1:1
	v_pk_mul_f32 v[2:3], v[24:25], v[76:77] op_sel_hi:[1,0]
	v_add_u32_e32 v4, 0x840, v79
	ds_write2_b32 v4, v2, v3 offset1:1
	v_pk_mul_f32 v[2:3], v[26:27], v[76:77] op_sel_hi:[1,0]
	v_add_u32_e32 v4, 0x848, v79
	ds_write2_b32 v4, v2, v3 offset1:1
	v_pk_mul_f32 v[2:3], v[20:21], v[78:79] op_sel_hi:[1,0]
	v_add_u32_e32 v4, 0xc60, v79
	ds_write2_b32 v4, v2, v3 offset1:1
	v_pk_mul_f32 v[2:3], v[22:23], v[78:79] op_sel_hi:[1,0]
	v_add_u32_e32 v4, 0xc68, v79
	ds_write2_b32 v4, v2, v3 offset1:1
	v_pk_mul_f32 v[2:3], v[36:37], v[80:81] op_sel_hi:[1,0]
	v_add_u32_e32 v4, 0x1080, v79
	ds_write2_b32 v4, v2, v3 offset1:1
	v_pk_mul_f32 v[2:3], v[38:39], v[80:81] op_sel_hi:[1,0]
	v_add_u32_e32 v4, 0x1088, v79
	ds_write2_b32 v4, v2, v3 offset1:1
	v_pk_mul_f32 v[2:3], v[28:29], v[82:83] op_sel_hi:[1,0]
	v_add_u32_e32 v4, 0x14a0, v79
	ds_write2_b32 v4, v2, v3 offset1:1
	v_pk_mul_f32 v[2:3], v[30:31], v[82:83] op_sel_hi:[1,0]
	v_add_u32_e32 v4, 0x14a8, v79
	ds_write2_b32 v4, v2, v3 offset1:1
	s_waitcnt vmcnt(7)
	v_pk_mul_f32 v[2:3], v[48:49], v[84:85] op_sel_hi:[1,0]
	v_add_u32_e32 v4, 0x18c0, v79
	s_mul_hi_i32 s6, s6, 0x2e8ba2e9
	ds_write2_b32 v4, v2, v3 offset1:1
	v_pk_mul_f32 v[2:3], v[50:51], v[84:85] op_sel_hi:[1,0]
	v_add_u32_e32 v4, 0x18c8, v79
	s_lshr_b32 s10, s6, 31
	s_ashr_i32 s6, s6, 6
	ds_write2_b32 v4, v2, v3 offset1:1
	s_waitcnt vmcnt(6)
	v_pk_mul_f32 v[2:3], v[44:45], v[86:87] op_sel_hi:[1,0]
	v_add_u32_e32 v4, 0x1ce0, v79
	s_add_i32 s6, s6, s10
	ds_write2_b32 v4, v2, v3 offset1:1
	v_pk_mul_f32 v[2:3], v[46:47], v[86:87] op_sel_hi:[1,0]
	v_add_u32_e32 v4, 0x1ce8, v79
	s_lshl_b32 s10, s6, 6
	ds_write2_b32 v4, v2, v3 offset1:1
	s_mulk_i32 s6, 0xd400
	s_waitcnt lgkmcnt(0)
	s_add_i32 s6, s6, s7
	ds_read2_b32 v[6:7], v77 offset0:33 offset1:41
	ds_read2_b32 v[12:13], v77 offset1:8
	ds_read2_b32 v[14:15], v77 offset0:66 offset1:74
	ds_read2_b32 v[20:21], v77 offset0:99 offset1:107
	ds_read2_b32 v[22:23], v77 offset0:132 offset1:140
	ds_read2_b32 v[24:25], v77 offset0:165 offset1:173
	ds_read2_b32 v[26:27], v77 offset0:198 offset1:206
	ds_read2_b32 v[28:29], v77 offset0:231 offset1:239
	v_add_u32_e32 v38, s6, v83
	s_waitcnt lgkmcnt(6)
	v_cvt_pk_bf16_f32 v2, v12, v6
	v_add_u32_e32 v6, 0xffffea00, v38
	v_cmp_lt_i32_e32 vcc, s16, v38
	s_waitcnt lgkmcnt(4)
	v_cvt_pk_bf16_f32 v3, v14, v20
	s_ashr_i32 s11, s10, 31
	v_cndmask_b32_e32 v6, v38, v6, vcc
	v_lshlrev_b32_e32 v12, 1, v6
	v_and_b32_e32 v12, 0xffffff00, v12
	v_cndmask_b32_e32 v14, 0, v81, vcc
	v_and_b32_e32 v6, 0x67, v6
	v_or3_b32 v36, v6, v14, v12
	v_ashrrev_i32_e32 v37, 31, v36
	v_lshl_add_u64 v[30:31], s[10:11], 1, v[70:71]
	v_lshlrev_b64 v[36:37], 12, v[36:37]
	s_waitcnt lgkmcnt(2)
	v_cvt_pk_bf16_f32 v4, v22, v24
	s_waitcnt lgkmcnt(0)
	v_cvt_pk_bf16_f32 v5, v26, v28
	v_lshl_add_u64 v[36:37], v[30:31], 0, v[36:37]
	v_add_u32_e32 v6, 8, v38
	global_store_dwordx4 v[36:37], v[2:5], off
	v_cmp_lt_i32_e32 vcc, s16, v6
	s_waitcnt vmcnt(3)
	v_mov_b64_e32 v[48:49], v[60:61]
	v_cvt_pk_bf16_f32 v2, v13, v7
	v_add_u32_e32 v7, 0xffffea08, v38
	v_cndmask_b32_e32 v6, v6, v7, vcc
	v_lshlrev_b32_e32 v7, 1, v6
	v_and_b32_e32 v7, 0xffffff00, v7
	v_cndmask_b32_e32 v12, 0, v81, vcc
	v_and_b32_e32 v6, 0x6f, v6
	v_or3_b32 v6, v6, v12, v7
	v_ashrrev_i32_e32 v7, 31, v6
	v_lshlrev_b64 v[6:7], 12, v[6:7]
	v_cvt_pk_bf16_f32 v3, v15, v21
	v_cvt_pk_bf16_f32 v4, v23, v25
	v_cvt_pk_bf16_f32 v5, v27, v29
	v_lshl_add_u64 v[6:7], v[30:31], 0, v[6:7]
	ds_read2_b32 v[12:13], v77 offset0:16 offset1:24
	ds_read2_b32 v[14:15], v77 offset0:49 offset1:57
	ds_read2_b32 v[20:21], v77 offset0:82 offset1:90
	ds_read2_b32 v[22:23], v77 offset0:115 offset1:123
	ds_read2_b32 v[24:25], v77 offset0:148 offset1:156
	ds_read2_b32 v[26:27], v77 offset0:181 offset1:189
	ds_read2_b32 v[28:29], v77 offset0:214 offset1:222
	ds_read2_b32 v[36:37], v77 offset0:247 offset1:255
	global_store_dwordx4 v[6:7], v[2:5], off
	v_add_u32_e32 v6, 16, v38
	v_add_u32_e32 v7, 0xffffea10, v38
	v_cmp_lt_i32_e32 vcc, s16, v6
	s_waitcnt lgkmcnt(6)
	v_cvt_pk_bf16_f32 v2, v12, v14
	s_waitcnt lgkmcnt(4)
	v_cvt_pk_bf16_f32 v3, v20, v22
	v_cndmask_b32_e32 v6, v6, v7, vcc
	v_lshlrev_b32_e32 v7, 1, v6
	v_and_b32_e32 v7, 0xffffff00, v7
	v_cndmask_b32_e32 v12, 0, v81, vcc
	v_and_b32_e32 v6, 0x77, v6
	v_or3_b32 v6, v6, v12, v7
	v_ashrrev_i32_e32 v7, 31, v6
	v_lshlrev_b64 v[6:7], 12, v[6:7]
	s_waitcnt lgkmcnt(2)
	v_cvt_pk_bf16_f32 v4, v24, v26
	s_waitcnt lgkmcnt(0)
	v_cvt_pk_bf16_f32 v5, v28, v36
	v_lshl_add_u64 v[6:7], v[30:31], 0, v[6:7]
	global_store_dwordx4 v[6:7], v[2:5], off
	s_waitcnt vmcnt(4)
	v_mov_b64_e32 v[44:45], v[64:65]
	v_add_u32_e32 v83, s12, v83
	v_add_u32_e32 v2, 24, v38
	v_add_u32_e32 v3, 0xffffea18, v38
	v_cmp_lt_i32_e32 vcc, s16, v2
	v_cvt_pk_bf16_f32 v5, v29, v37
	v_mov_b64_e32 v[36:37], v[52:53]
	v_cndmask_b32_e32 v2, v2, v3, vcc
	v_lshlrev_b32_e32 v3, 1, v2
	v_and_b32_e32 v3, 0xffffff00, v3
	v_cndmask_b32_e32 v4, 0, v81, vcc
	v_and_b32_e32 v2, 0x7f, v2
	v_or3_b32 v6, v2, v4, v3
	v_ashrrev_i32_e32 v7, 31, v6
	v_lshlrev_b64 v[6:7], 12, v[6:7]
	v_cvt_pk_bf16_f32 v2, v13, v15
	v_cvt_pk_bf16_f32 v3, v21, v23
	v_cvt_pk_bf16_f32 v4, v25, v27
	v_lshl_add_u64 v[6:7], v[30:31], 0, v[6:7]
	global_store_dwordx4 v[6:7], v[2:5], off sc0 sc1
	s_waitcnt lgkmcnt(0)
	v_mov_b64_e32 v[12:13], v[16:17]
	v_mov_b64_e32 v[24:25], v[32:33]
	v_mov_b64_e32 v[4:5], v[8:9]
	v_mov_b64_e32 v[20:21], v[40:41]
	v_mov_b64_e32 v[28:29], v[56:57]
	s_add_i32 s17, s17, s12
	v_add_u32_e32 v73, s12, v73
	s_andn2_b64 vcc, exec, s[8:9]
	s_mov_b32 s6, s18
	v_mov_b64_e32 v[14:15], v[18:19]
	v_mov_b64_e32 v[6:7], v[10:11]
	v_mov_b64_e32 v[26:27], v[34:35]
	v_mov_b64_e32 v[22:23], v[42:43]
	v_mov_b64_e32 v[38:39], v[54:55]
	v_mov_b64_e32 v[30:31], v[58:59]
	v_mov_b64_e32 v[50:51], v[62:63]
	v_mov_b64_e32 v[46:47], v[66:67]
	v_mov_b32_e32 v72, v85
	v_mov_b32_e32 v74, v87
	v_mov_b32_e32 v76, v89
	v_mov_b32_e32 v78, v94
	v_mov_b32_e32 v80, v95
	v_mov_b32_e32 v82, v96
	v_mov_b32_e32 v84, v97
	s_waitcnt vmcnt(4)
	v_mov_b32_e32 v86, v1
	s_cbranch_vccz .LBB0_1223

; #define LAS __attribute__((address_space(3)))
; __device__ __forceinline__ unsigned cvtpk(float lo, float hi) { f32x2 v = {lo, hi}; bf16x2_t b = __builtin_convertvector(v, bf16x2_t); return __builtin_bit_cast(unsigned, b); }
; __device__ __forceinline__ void witem_store(const WItem& w, int K, bf16_t* WT, int kvperm, LAS float* scr, int item, int nblk, int lane) {
;     ...
;     for (int i = 0; i < 8; ++i) { LAS float* d = scr + (8 * i + rr) * 33 + col; const float g = w.g[i]; d[0] = w.v[i].x * g; d[1] = w.v[i].y * g; d[2] = w.v[i].z * g; d[3] = w.v[i].w * g; }
;     asm volatile("s_waitcnt lgkmcnt(0)" ::: "memory");
;     const int c = lane & 7;
; #pragma unroll
;     for (int j = 0; j < 4; ++j) { const int n = (lane >> 3) + 8 * j; const LAS float* s = scr + (8 * c) * 33 + n;
;         u32x4 o; o.x = cvtpk(s[0 * 33], s[1 * 33]); o.y = cvtpk(s[2 * 33], s[3 * 33]); o.z = cvtpk(s[4 * 33], s[5 * 33]); o.w = cvtpk(s[6 * 33], s[7 * 33]);
;         int nr = n0 + n; if (kvperm == 1) { const int hh = nr >> 8, ww = nr & 255; nr = (ww < 128) ? hh * 128 + ww : 2048 + hh * 128 + (ww - 128); }
;         else if (kvperm == 2) { const int isv = nr >= 5632, f = isv ? nr - 5632 : nr; nr = (f >> 7) * 256 + isv * 128 + (f & 127); }
;         *(u32x4*)(WT + (size_t)nr * K + k0 + 8 * c) = o; }
;     ...
;     while (it < i1) {
;         cur = nxt;
;         const int nit = it + NGW;
;         if (nit < i1) witem_load(nxt, W, N, gk, nit, nblk, lane);
;         witem_store(cur, K, WT, kvperm, scr, it, nblk, lane);
;         it = nit;
;     }
.LBB0_1491:
	v_pk_mul_f32 v[2:3], v[16:17], v[72:73] op_sel_hi:[1,0]
	ds_write2_b32 v85, v2, v3 offset1:1
	v_pk_mul_f32 v[2:3], v[18:19], v[72:73] op_sel_hi:[1,0]
	ds_write2_b32 v85, v2, v3 offset0:2 offset1:3
	v_pk_mul_f32 v[2:3], v[4:5], v[74:75] op_sel_hi:[1,0]
	v_add_u32_e32 v4, 0x420, v85
	ds_write2_b32 v4, v2, v3 offset1:1
	v_pk_mul_f32 v[2:3], v[6:7], v[74:75] op_sel_hi:[1,0]
	v_add_u32_e32 v4, 0x428, v85
	ds_write2_b32 v4, v2, v3 offset1:1
	v_pk_mul_f32 v[2:3], v[24:25], v[76:77] op_sel_hi:[1,0]
	v_add_u32_e32 v4, 0x840, v85
	ds_write2_b32 v4, v2, v3 offset1:1
	v_pk_mul_f32 v[2:3], v[26:27], v[76:77] op_sel_hi:[1,0]
	v_add_u32_e32 v4, 0x848, v85
	ds_write2_b32 v4, v2, v3 offset1:1
	v_pk_mul_f32 v[2:3], v[20:21], v[78:79] op_sel_hi:[1,0]
	v_add_u32_e32 v4, 0xc60, v85
	ds_write2_b32 v4, v2, v3 offset1:1
	v_pk_mul_f32 v[2:3], v[22:23], v[78:79] op_sel_hi:[1,0]
	v_add_u32_e32 v4, 0xc68, v85
	ds_write2_b32 v4, v2, v3 offset1:1
	v_pk_mul_f32 v[2:3], v[36:37], v[80:81] op_sel_hi:[1,0]
	v_add_u32_e32 v4, 0x1080, v85
	ds_write2_b32 v4, v2, v3 offset1:1
	v_pk_mul_f32 v[2:3], v[38:39], v[80:81] op_sel_hi:[1,0]
	v_add_u32_e32 v4, 0x1088, v85
	ds_write2_b32 v4, v2, v3 offset1:1
	v_pk_mul_f32 v[2:3], v[32:33], v[82:83] op_sel_hi:[1,0]
	v_add_u32_e32 v4, 0x14a0, v85
	s_mul_hi_i32 s16, s27, 0x2e8ba2e9
	ds_write2_b32 v4, v2, v3 offset1:1
	v_pk_mul_f32 v[2:3], v[34:35], v[82:83] op_sel_hi:[1,0]
	v_add_u32_e32 v4, 0x14a8, v85
	s_lshr_b32 s17, s16, 31
	s_ashr_i32 s16, s16, 6
	ds_write2_b32 v4, v2, v3 offset1:1
	v_pk_mul_f32 v[2:3], v[52:53], v[84:85] op_sel_hi:[1,0]
	v_add_u32_e32 v4, 0x18c0, v85
	s_add_i32 s27, s16, s17
	ds_write2_b32 v4, v2, v3 offset1:1
	v_pk_mul_f32 v[2:3], v[54:55], v[84:85] op_sel_hi:[1,0]
	v_add_u32_e32 v4, 0x18c8, v85
	s_lshl_b32 s16, s27, 6
	ds_write2_b32 v4, v2, v3 offset1:1
	v_pk_mul_f32 v[2:3], v[44:45], v[86:87] op_sel_hi:[1,0]
	v_add_u32_e32 v4, 0x1ce0, v85
	ds_write2_b32 v4, v2, v3 offset1:1
	v_pk_mul_f32 v[2:3], v[46:47], v[86:87] op_sel_hi:[1,0]
	v_add_u32_e32 v4, 0x1ce8, v85
	s_ashr_i32 s17, s16, 31
	ds_write2_b32 v4, v2, v3 offset1:1
	v_lshl_add_u64 v[34:35], s[16:17], 1, v[70:71]
	s_mul_i32 s16, s27, 0xffffd400
	s_waitcnt lgkmcnt(0)
	s_add_i32 s16, s16, s22
	ds_read2_b32 v[6:7], v83 offset0:33 offset1:41
	ds_read2_b32 v[16:17], v83 offset1:8
	ds_read2_b32 v[18:19], v83 offset0:66 offset1:74
	ds_read2_b32 v[20:21], v83 offset0:99 offset1:107
	ds_read2_b32 v[22:23], v83 offset0:132 offset1:140
	ds_read2_b32 v[24:25], v83 offset0:165 offset1:173
	ds_read2_b32 v[26:27], v83 offset0:198 offset1:206
	ds_read2_b32 v[32:33], v83 offset0:231 offset1:239
	v_add_u32_e32 v38, s16, v94
	s_waitcnt lgkmcnt(6)
	v_cvt_pk_bf16_f32 v2, v16, v6
	v_add_u32_e32 v6, 0xffffea00, v38
	v_cmp_lt_i32_e32 vcc, s28, v38
	s_waitcnt lgkmcnt(4)
	v_cvt_pk_bf16_f32 v3, v18, v20
	s_waitcnt lgkmcnt(2)
	v_cvt_pk_bf16_f32 v4, v22, v24
	v_cndmask_b32_e32 v6, v38, v6, vcc
	v_lshlrev_b32_e32 v16, 1, v6
	v_and_b32_e32 v16, 0xffffff00, v16
	v_cndmask_b32_e32 v18, 0, v87, vcc
	v_and_b32_e32 v6, 0x67, v6
	v_or3_b32 v36, v6, v18, v16
	v_ashrrev_i32_e32 v37, 31, v36
	v_lshlrev_b64 v[36:37], 12, v[36:37]
	s_waitcnt lgkmcnt(0)
	v_cvt_pk_bf16_f32 v5, v26, v32
	v_lshl_add_u64 v[36:37], v[34:35], 0, v[36:37]
	v_add_u32_e32 v6, 8, v38
	global_store_dwordx4 v[36:37], v[2:5], off
	v_cmp_lt_i32_e32 vcc, s28, v6
	s_waitcnt vmcnt(3)
	v_mov_b64_e32 v[52:53], v[60:61]
	v_cvt_pk_bf16_f32 v2, v17, v7
	v_add_u32_e32 v7, 0xffffea08, v38
	v_cndmask_b32_e32 v6, v6, v7, vcc
	v_lshlrev_b32_e32 v7, 1, v6
	v_and_b32_e32 v7, 0xffffff00, v7
	v_cndmask_b32_e32 v16, 0, v87, vcc
	v_and_b32_e32 v6, 0x6f, v6
	v_or3_b32 v6, v6, v16, v7
	v_ashrrev_i32_e32 v7, 31, v6
	v_lshlrev_b64 v[6:7], 12, v[6:7]
	v_cvt_pk_bf16_f32 v3, v19, v21
	v_cvt_pk_bf16_f32 v4, v23, v25
	v_cvt_pk_bf16_f32 v5, v27, v33
	v_lshl_add_u64 v[6:7], v[34:35], 0, v[6:7]
	ds_read2_b32 v[16:17], v83 offset0:16 offset1:24
	ds_read2_b32 v[18:19], v83 offset0:49 offset1:57
	ds_read2_b32 v[20:21], v83 offset0:82 offset1:90
	ds_read2_b32 v[22:23], v83 offset0:115 offset1:123
	ds_read2_b32 v[24:25], v83 offset0:148 offset1:156
	ds_read2_b32 v[26:27], v83 offset0:181 offset1:189
	ds_read2_b32 v[32:33], v83 offset0:214 offset1:222
	ds_read2_b32 v[36:37], v83 offset0:247 offset1:255
	global_store_dwordx4 v[6:7], v[2:5], off
	v_add_u32_e32 v6, 16, v38
	v_add_u32_e32 v7, 0xffffea10, v38
	v_cmp_lt_i32_e32 vcc, s28, v6
	s_waitcnt lgkmcnt(6)
	v_cvt_pk_bf16_f32 v2, v16, v18
	s_waitcnt lgkmcnt(4)
	v_cvt_pk_bf16_f32 v3, v20, v22
	v_cndmask_b32_e32 v6, v6, v7, vcc
	v_lshlrev_b32_e32 v7, 1, v6
	v_and_b32_e32 v7, 0xffffff00, v7
	v_cndmask_b32_e32 v16, 0, v87, vcc
	v_and_b32_e32 v6, 0x77, v6
	v_or3_b32 v6, v6, v16, v7
	v_ashrrev_i32_e32 v7, 31, v6
	v_lshlrev_b64 v[6:7], 12, v[6:7]
	s_waitcnt lgkmcnt(2)
	v_cvt_pk_bf16_f32 v4, v24, v26
	s_waitcnt lgkmcnt(0)
	v_cvt_pk_bf16_f32 v5, v32, v36
	v_lshl_add_u64 v[6:7], v[34:35], 0, v[6:7]
	global_store_dwordx4 v[6:7], v[2:5], off
	s_waitcnt vmcnt(4)
	v_mov_b64_e32 v[44:45], v[64:65]
	v_add_u32_e32 v94, s23, v94
	v_add_u32_e32 v2, 24, v38
	v_add_u32_e32 v3, 0xffffea18, v38
	v_cmp_lt_i32_e32 vcc, s28, v2
	v_cvt_pk_bf16_f32 v5, v33, v37
	v_mov_b64_e32 v[36:37], v[48:49]
	v_cndmask_b32_e32 v2, v2, v3, vcc
	v_lshlrev_b32_e32 v3, 1, v2
	v_and_b32_e32 v3, 0xffffff00, v3
	v_cndmask_b32_e32 v4, 0, v87, vcc
	v_and_b32_e32 v2, 0x7f, v2
	v_or3_b32 v6, v2, v4, v3
	v_ashrrev_i32_e32 v7, 31, v6
	v_lshlrev_b64 v[6:7], 12, v[6:7]
	v_cvt_pk_bf16_f32 v2, v17, v19
	v_cvt_pk_bf16_f32 v3, v21, v23
	v_cvt_pk_bf16_f32 v4, v25, v27
	v_lshl_add_u64 v[6:7], v[34:35], 0, v[6:7]
	global_store_dwordx4 v[6:7], v[2:5], off sc0 sc1
	s_waitcnt lgkmcnt(0)
	v_mov_b64_e32 v[18:19], v[14:15]
	v_mov_b64_e32 v[24:25], v[28:29]
	v_mov_b64_e32 v[4:5], v[8:9]
	v_mov_b64_e32 v[20:21], v[40:41]
	v_mov_b64_e32 v[32:33], v[56:57]
	s_add_i32 s29, s29, s23
	v_add_u32_e32 v73, s23, v73
	s_andn2_b64 vcc, exec, s[14:15]
	s_mov_b32 s27, s30
	v_mov_b64_e32 v[16:17], v[12:13]
	v_mov_b64_e32 v[6:7], v[10:11]
	v_mov_b64_e32 v[26:27], v[30:31]
	v_mov_b64_e32 v[22:23], v[42:43]
	v_mov_b64_e32 v[38:39], v[50:51]
	v_mov_b64_e32 v[34:35], v[58:59]
	v_mov_b64_e32 v[54:55], v[62:63]
	v_mov_b64_e32 v[46:47], v[66:67]
	v_mov_b32_e32 v72, v89
	v_mov_b32_e32 v74, v95
	v_mov_b32_e32 v76, v96
	v_mov_b32_e32 v78, v97
	v_mov_b32_e32 v80, v98
	v_mov_b32_e32 v82, v99
	v_mov_b32_e32 v84, v100
	s_waitcnt vmcnt(4)
	v_mov_b32_e32 v86, v1
	s_cbranch_vccz .LBB0_1509

; #define LAS __attribute__((address_space(3)))
; __device__ __forceinline__ unsigned cvtpk(float lo, float hi) { f32x2 v = {lo, hi}; bf16x2_t b = __builtin_convertvector(v, bf16x2_t); return __builtin_bit_cast(unsigned, b); }
; __device__ __forceinline__ void witem_store(const WItem& w, int K, bf16_t* WT, int kvperm, LAS float* scr, int item, int nblk, int lane) {
;     ...
;     for (int i = 0; i < 8; ++i) { LAS float* d = scr + (8 * i + rr) * 33 + col; const float g = w.g[i]; d[0] = w.v[i].x * g; d[1] = w.v[i].y * g; d[2] = w.v[i].z * g; d[3] = w.v[i].w * g; }
;     asm volatile("s_waitcnt lgkmcnt(0)" ::: "memory");
;     const int c = lane & 7;
; #pragma unroll
;     for (int j = 0; j < 4; ++j) { const int n = (lane >> 3) + 8 * j; const LAS float* s = scr + (8 * c) * 33 + n;
;         u32x4 o; o.x = cvtpk(s[0 * 33], s[1 * 33]); o.y = cvtpk(s[2 * 33], s[3 * 33]); o.z = cvtpk(s[4 * 33], s[5 * 33]); o.w = cvtpk(s[6 * 33], s[7 * 33]);
;         int nr = n0 + n; if (kvperm == 1) { const int hh = nr >> 8, ww = nr & 255; nr = (ww < 128) ? hh * 128 + ww : 2048 + hh * 128 + (ww - 128); }
;         else if (kvperm == 2) { const int isv = nr >= 5632, f = isv ? nr - 5632 : nr; nr = (f >> 7) * 256 + isv * 128 + (f & 127); }
;         *(u32x4*)(WT + (size_t)nr * K + k0 + 8 * c) = o; }
;     ...
;     while (it < i1) {
;         cur = nxt;
;         const int nit = it + NGW;
;         if (nit < i1) witem_load(nxt, W, N, gk, nit, nblk, lane);
;         witem_store(cur, K, WT, kvperm, scr, it, nblk, lane);
;         it = nit;
;     }
.LBB0_1528:
	v_pk_mul_f32 v[2:3], v[16:17], v[72:73] op_sel_hi:[1,0]
	ds_write2_b32 v79, v2, v3 offset1:1
	v_pk_mul_f32 v[2:3], v[18:19], v[72:73] op_sel_hi:[1,0]
	ds_write2_b32 v79, v2, v3 offset0:2 offset1:3
	v_pk_mul_f32 v[2:3], v[4:5], v[74:75] op_sel_hi:[1,0]
	v_add_u32_e32 v4, 0x420, v79
	ds_write2_b32 v4, v2, v3 offset1:1
	v_pk_mul_f32 v[2:3], v[6:7], v[74:75] op_sel_hi:[1,0]
	v_add_u32_e32 v4, 0x428, v79
	ds_write2_b32 v4, v2, v3 offset1:1
	v_pk_mul_f32 v[2:3], v[24:25], v[76:77] op_sel_hi:[1,0]
	v_add_u32_e32 v4, 0x840, v79
	ds_write2_b32 v4, v2, v3 offset1:1
	v_pk_mul_f32 v[2:3], v[26:27], v[76:77] op_sel_hi:[1,0]
	v_add_u32_e32 v4, 0x848, v79
	ds_write2_b32 v4, v2, v3 offset1:1
	v_pk_mul_f32 v[2:3], v[20:21], v[78:79] op_sel_hi:[1,0]
	v_add_u32_e32 v4, 0xc60, v79
	ds_write2_b32 v4, v2, v3 offset1:1
	v_pk_mul_f32 v[2:3], v[22:23], v[78:79] op_sel_hi:[1,0]
	v_add_u32_e32 v4, 0xc68, v79
	ds_write2_b32 v4, v2, v3 offset1:1
	v_pk_mul_f32 v[2:3], v[36:37], v[80:81] op_sel_hi:[1,0]
	v_add_u32_e32 v4, 0x1080, v79
	ds_write2_b32 v4, v2, v3 offset1:1
	v_pk_mul_f32 v[2:3], v[38:39], v[80:81] op_sel_hi:[1,0]
	v_add_u32_e32 v4, 0x1088, v79
	ds_write2_b32 v4, v2, v3 offset1:1
	v_pk_mul_f32 v[2:3], v[32:33], v[82:83] op_sel_hi:[1,0]
	v_add_u32_e32 v4, 0x14a0, v79
	s_mul_hi_i32 s10, s15, 0x2e8ba2e9
	ds_write2_b32 v4, v2, v3 offset1:1
	v_pk_mul_f32 v[2:3], v[34:35], v[82:83] op_sel_hi:[1,0]
	v_add_u32_e32 v4, 0x14a8, v79
	s_lshr_b32 s11, s10, 31
	s_ashr_i32 s10, s10, 6
	ds_write2_b32 v4, v2, v3 offset1:1
	s_waitcnt vmcnt(7)
	v_pk_mul_f32 v[2:3], v[52:53], v[84:85] op_sel_hi:[1,0]
	v_add_u32_e32 v4, 0x18c0, v79
	s_add_i32 s15, s10, s11
	ds_write2_b32 v4, v2, v3 offset1:1
	v_pk_mul_f32 v[2:3], v[54:55], v[84:85] op_sel_hi:[1,0]
	v_add_u32_e32 v4, 0x18c8, v79
	s_lshl_b32 s10, s15, 6
	ds_write2_b32 v4, v2, v3 offset1:1
	s_waitcnt vmcnt(6)
	v_pk_mul_f32 v[2:3], v[44:45], v[86:87] op_sel_hi:[1,0]
	v_add_u32_e32 v4, 0x1ce0, v79
	ds_write2_b32 v4, v2, v3 offset1:1
	v_pk_mul_f32 v[2:3], v[46:47], v[86:87] op_sel_hi:[1,0]
	v_add_u32_e32 v4, 0x1ce8, v79
	s_ashr_i32 s11, s10, 31
	ds_write2_b32 v4, v2, v3 offset1:1
	v_lshl_add_u64 v[34:35], s[10:11], 1, v[70:71]
	s_mul_i32 s10, s15, 0xffffd400
	s_waitcnt lgkmcnt(0)
	s_add_i32 s10, s10, s2
	ds_read2_b32 v[6:7], v75 offset0:33 offset1:41
	ds_read2_b32 v[16:17], v75 offset1:8
	ds_read2_b32 v[18:19], v75 offset0:66 offset1:74
	ds_read2_b32 v[20:21], v75 offset0:99 offset1:107
	ds_read2_b32 v[22:23], v75 offset0:132 offset1:140
	ds_read2_b32 v[24:25], v75 offset0:165 offset1:173
	ds_read2_b32 v[26:27], v75 offset0:198 offset1:206
	ds_read2_b32 v[32:33], v75 offset0:231 offset1:239
	v_add_u32_e32 v38, s10, v83
	s_waitcnt lgkmcnt(6)
	v_cvt_pk_bf16_f32 v2, v16, v6
	v_add_u32_e32 v6, 0xffffea00, v38
	v_cmp_lt_i32_e32 vcc, s14, v38
	s_waitcnt lgkmcnt(4)
	v_cvt_pk_bf16_f32 v3, v18, v20
	s_waitcnt lgkmcnt(2)
	v_cvt_pk_bf16_f32 v4, v22, v24
	v_cndmask_b32_e32 v6, v38, v6, vcc
	v_lshlrev_b32_e32 v16, 1, v6
	v_and_b32_e32 v16, 0xffffff00, v16
	v_cndmask_b32_e32 v18, 0, v81, vcc
	v_and_b32_e32 v6, 0x67, v6
	v_or3_b32 v36, v6, v18, v16
	v_ashrrev_i32_e32 v37, 31, v36
	v_lshlrev_b64 v[36:37], 12, v[36:37]
	s_waitcnt lgkmcnt(0)
	v_cvt_pk_bf16_f32 v5, v26, v32
	v_lshl_add_u64 v[36:37], v[34:35], 0, v[36:37]
	v_add_u32_e32 v6, 8, v38
	global_store_dwordx4 v[36:37], v[2:5], off
	v_cmp_lt_i32_e32 vcc, s14, v6
	s_waitcnt vmcnt(3)
	v_mov_b64_e32 v[52:53], v[60:61]
	v_cvt_pk_bf16_f32 v2, v17, v7
	v_add_u32_e32 v7, 0xffffea08, v38
	v_cndmask_b32_e32 v6, v6, v7, vcc
	v_lshlrev_b32_e32 v7, 1, v6
	v_and_b32_e32 v7, 0xffffff00, v7
	v_cndmask_b32_e32 v16, 0, v81, vcc
	v_and_b32_e32 v6, 0x6f, v6
	v_or3_b32 v6, v6, v16, v7
	v_ashrrev_i32_e32 v7, 31, v6
	v_lshlrev_b64 v[6:7], 12, v[6:7]
	v_cvt_pk_bf16_f32 v3, v19, v21
	v_cvt_pk_bf16_f32 v4, v23, v25
	v_cvt_pk_bf16_f32 v5, v27, v33
	v_lshl_add_u64 v[6:7], v[34:35], 0, v[6:7]
	ds_read2_b32 v[16:17], v75 offset0:16 offset1:24
	ds_read2_b32 v[18:19], v75 offset0:49 offset1:57
	ds_read2_b32 v[20:21], v75 offset0:82 offset1:90
	ds_read2_b32 v[22:23], v75 offset0:115 offset1:123
	ds_read2_b32 v[24:25], v75 offset0:148 offset1:156
	ds_read2_b32 v[26:27], v75 offset0:181 offset1:189
	ds_read2_b32 v[32:33], v75 offset0:214 offset1:222
	ds_read2_b32 v[36:37], v75 offset0:247 offset1:255
	global_store_dwordx4 v[6:7], v[2:5], off
	v_add_u32_e32 v6, 16, v38
	v_add_u32_e32 v7, 0xffffea10, v38
	v_cmp_lt_i32_e32 vcc, s14, v6
	s_waitcnt lgkmcnt(6)
	v_cvt_pk_bf16_f32 v2, v16, v18
	s_waitcnt lgkmcnt(4)
	v_cvt_pk_bf16_f32 v3, v20, v22
	v_cndmask_b32_e32 v6, v6, v7, vcc
	v_lshlrev_b32_e32 v7, 1, v6
	v_and_b32_e32 v7, 0xffffff00, v7
	v_cndmask_b32_e32 v16, 0, v81, vcc
	v_and_b32_e32 v6, 0x77, v6
	v_or3_b32 v6, v6, v16, v7
	v_ashrrev_i32_e32 v7, 31, v6
	v_lshlrev_b64 v[6:7], 12, v[6:7]
	s_waitcnt lgkmcnt(2)
	v_cvt_pk_bf16_f32 v4, v24, v26
	s_waitcnt lgkmcnt(0)
	v_cvt_pk_bf16_f32 v5, v32, v36
	v_lshl_add_u64 v[6:7], v[34:35], 0, v[6:7]
	global_store_dwordx4 v[6:7], v[2:5], off
	s_waitcnt vmcnt(4)
	v_mov_b64_e32 v[44:45], v[64:65]
	v_add_u32_e32 v83, s6, v83
	v_add_u32_e32 v2, 24, v38
	v_add_u32_e32 v3, 0xffffea18, v38
	v_cmp_lt_i32_e32 vcc, s14, v2
	v_cvt_pk_bf16_f32 v5, v33, v37
	v_mov_b64_e32 v[36:37], v[48:49]
	v_cndmask_b32_e32 v2, v2, v3, vcc
	v_lshlrev_b32_e32 v3, 1, v2
	v_and_b32_e32 v3, 0xffffff00, v3
	v_cndmask_b32_e32 v4, 0, v81, vcc
	v_and_b32_e32 v2, 0x7f, v2
	v_or3_b32 v6, v2, v4, v3
	v_ashrrev_i32_e32 v7, 31, v6
	v_lshlrev_b64 v[6:7], 12, v[6:7]
	v_cvt_pk_bf16_f32 v2, v17, v19
	v_cvt_pk_bf16_f32 v3, v21, v23
	v_cvt_pk_bf16_f32 v4, v25, v27
	v_lshl_add_u64 v[6:7], v[34:35], 0, v[6:7]
	global_store_dwordx4 v[6:7], v[2:5], off sc0 sc1
	s_waitcnt lgkmcnt(0)
	v_mov_b64_e32 v[18:19], v[14:15]
	v_mov_b64_e32 v[24:25], v[28:29]
	v_mov_b64_e32 v[4:5], v[8:9]
	v_mov_b64_e32 v[20:21], v[40:41]
	v_mov_b64_e32 v[32:33], v[56:57]
	s_add_i32 s16, s16, s6
	v_add_u32_e32 v73, s6, v73
	s_andn2_b64 vcc, exec, s[0:1]
	s_mov_b32 s15, s17
	v_mov_b64_e32 v[16:17], v[12:13]
	v_mov_b64_e32 v[6:7], v[10:11]
	v_mov_b64_e32 v[26:27], v[30:31]
	v_mov_b64_e32 v[22:23], v[42:43]
	v_mov_b64_e32 v[38:39], v[50:51]
	v_mov_b64_e32 v[34:35], v[58:59]
	v_mov_b64_e32 v[54:55], v[62:63]
	v_mov_b64_e32 v[46:47], v[66:67]
	v_mov_b32_e32 v72, v85
	v_mov_b32_e32 v74, v87
	v_mov_b32_e32 v76, v89
	v_mov_b32_e32 v78, v94
	v_mov_b32_e32 v80, v95
	v_mov_b32_e32 v82, v96
	v_mov_b32_e32 v84, v97
	s_waitcnt vmcnt(4)
	v_mov_b32_e32 v86, v1
	s_cbranch_vccz .LBB0_1546

; #define LAS __attribute__((address_space(3)))
; __device__ __forceinline__ unsigned cvtpk(float lo, float hi) { f32x2 v = {lo, hi}; bf16x2_t b = __builtin_convertvector(v, bf16x2_t); return __builtin_bit_cast(unsigned, b); }
; __device__ __forceinline__ void witem_store(const WItem& w, int K, bf16_t* WT, int kvperm, LAS float* scr, int item, int nblk, int lane) {
;     ...
;     for (int i = 0; i < 8; ++i) { LAS float* d = scr + (8 * i + rr) * 33 + col; const float g = w.g[i]; d[0] = w.v[i].x * g; d[1] = w.v[i].y * g; d[2] = w.v[i].z * g; d[3] = w.v[i].w * g; }
;     asm volatile("s_waitcnt lgkmcnt(0)" ::: "memory");
;     const int c = lane & 7;
; #pragma unroll
;     for (int j = 0; j < 4; ++j) { const int n = (lane >> 3) + 8 * j; const LAS float* s = scr + (8 * c) * 33 + n;
;         u32x4 o; o.x = cvtpk(s[0 * 33], s[1 * 33]); o.y = cvtpk(s[2 * 33], s[3 * 33]); o.z = cvtpk(s[4 * 33], s[5 * 33]); o.w = cvtpk(s[6 * 33], s[7 * 33]);
;         int nr = n0 + n; if (kvperm == 1) { const int hh = nr >> 8, ww = nr & 255; nr = (ww < 128) ? hh * 128 + ww : 2048 + hh * 128 + (ww - 128); }
;         else if (kvperm == 2) { const int isv = nr >= 5632, f = isv ? nr - 5632 : nr; nr = (f >> 7) * 256 + isv * 128 + (f & 127); }
;         *(u32x4*)(WT + (size_t)nr * K + k0 + 8 * c) = o; }
;     ...
;     while (it < i1) {
;         cur = nxt;
;         const int nit = it + NGW;
;         if (nit < i1) witem_load(nxt, W, N, gk, nit, nblk, lane);
;         witem_store(cur, K, WT, kvperm, scr, it, nblk, lane);
;         it = nit;
;     }
.LBB0_1844:
	v_pk_mul_f32 v[2:3], v[12:13], v[72:73] op_sel_hi:[1,0]
	ds_write2_b32 v79, v2, v3 offset1:1
	v_pk_mul_f32 v[2:3], v[14:15], v[72:73] op_sel_hi:[1,0]
	ds_write2_b32 v79, v2, v3 offset0:2 offset1:3
	v_pk_mul_f32 v[2:3], v[4:5], v[74:75] op_sel_hi:[1,0]
	v_add_u32_e32 v4, 0x420, v79
	ds_write2_b32 v4, v2, v3 offset1:1
	v_pk_mul_f32 v[2:3], v[6:7], v[74:75] op_sel_hi:[1,0]
	v_add_u32_e32 v4, 0x428, v79
	ds_write2_b32 v4, v2, v3 offset1:1
	v_pk_mul_f32 v[2:3], v[24:25], v[76:77] op_sel_hi:[1,0]
	v_add_u32_e32 v4, 0x840, v79
	ds_write2_b32 v4, v2, v3 offset1:1
	v_pk_mul_f32 v[2:3], v[26:27], v[76:77] op_sel_hi:[1,0]
	v_add_u32_e32 v4, 0x848, v79
	ds_write2_b32 v4, v2, v3 offset1:1
	v_pk_mul_f32 v[2:3], v[20:21], v[78:79] op_sel_hi:[1,0]
	v_add_u32_e32 v4, 0xc60, v79
	ds_write2_b32 v4, v2, v3 offset1:1
	v_pk_mul_f32 v[2:3], v[22:23], v[78:79] op_sel_hi:[1,0]
	v_add_u32_e32 v4, 0xc68, v79
	ds_write2_b32 v4, v2, v3 offset1:1
	v_pk_mul_f32 v[2:3], v[36:37], v[80:81] op_sel_hi:[1,0]
	v_add_u32_e32 v4, 0x1080, v79
	ds_write2_b32 v4, v2, v3 offset1:1
	v_pk_mul_f32 v[2:3], v[38:39], v[80:81] op_sel_hi:[1,0]
	v_add_u32_e32 v4, 0x1088, v79
	ds_write2_b32 v4, v2, v3 offset1:1
	v_pk_mul_f32 v[2:3], v[28:29], v[82:83] op_sel_hi:[1,0]
	v_add_u32_e32 v4, 0x14a0, v79
	ds_write2_b32 v4, v2, v3 offset1:1
	v_pk_mul_f32 v[2:3], v[30:31], v[82:83] op_sel_hi:[1,0]
	v_add_u32_e32 v4, 0x14a8, v79
	ds_write2_b32 v4, v2, v3 offset1:1
	s_waitcnt vmcnt(7)
	v_pk_mul_f32 v[2:3], v[48:49], v[84:85] op_sel_hi:[1,0]
	v_add_u32_e32 v4, 0x18c0, v79
	s_mul_hi_i32 s6, s6, 0x2e8ba2e9
	ds_write2_b32 v4, v2, v3 offset1:1
	v_pk_mul_f32 v[2:3], v[50:51], v[84:85] op_sel_hi:[1,0]
	v_add_u32_e32 v4, 0x18c8, v79
	s_lshr_b32 s12, s6, 31
	s_ashr_i32 s6, s6, 6
	ds_write2_b32 v4, v2, v3 offset1:1
	s_waitcnt vmcnt(6)
	v_pk_mul_f32 v[2:3], v[44:45], v[86:87] op_sel_hi:[1,0]
	v_add_u32_e32 v4, 0x1ce0, v79
	s_add_i32 s6, s6, s12
	ds_write2_b32 v4, v2, v3 offset1:1
	v_pk_mul_f32 v[2:3], v[46:47], v[86:87] op_sel_hi:[1,0]
	v_add_u32_e32 v4, 0x1ce8, v79
	s_lshl_b32 s12, s6, 6
	ds_write2_b32 v4, v2, v3 offset1:1
	s_mulk_i32 s6, 0xd400
	s_waitcnt lgkmcnt(0)
	s_add_i32 s6, s6, s7
	ds_read2_b32 v[6:7], v77 offset0:33 offset1:41
	ds_read2_b32 v[12:13], v77 offset1:8
	ds_read2_b32 v[14:15], v77 offset0:66 offset1:74
	ds_read2_b32 v[20:21], v77 offset0:99 offset1:107
	ds_read2_b32 v[22:23], v77 offset0:132 offset1:140
	ds_read2_b32 v[24:25], v77 offset0:165 offset1:173
	ds_read2_b32 v[26:27], v77 offset0:198 offset1:206
	ds_read2_b32 v[28:29], v77 offset0:231 offset1:239
	v_add_u32_e32 v38, s6, v83
	s_waitcnt lgkmcnt(6)
	v_cvt_pk_bf16_f32 v2, v12, v6
	v_add_u32_e32 v6, 0xffffea00, v38
	v_cmp_lt_i32_e32 vcc, s18, v38
	s_waitcnt lgkmcnt(4)
	v_cvt_pk_bf16_f32 v3, v14, v20
	s_ashr_i32 s13, s12, 31
	v_cndmask_b32_e32 v6, v38, v6, vcc
	v_lshlrev_b32_e32 v12, 1, v6
	v_and_b32_e32 v12, 0xffffff00, v12
	v_cndmask_b32_e32 v14, 0, v81, vcc
	v_and_b32_e32 v6, 0x67, v6
	v_or3_b32 v36, v6, v14, v12
	v_ashrrev_i32_e32 v37, 31, v36
	v_lshl_add_u64 v[30:31], s[12:13], 1, v[70:71]
	v_lshlrev_b64 v[36:37], 12, v[36:37]
	s_waitcnt lgkmcnt(2)
	v_cvt_pk_bf16_f32 v4, v22, v24
	s_waitcnt lgkmcnt(0)
	v_cvt_pk_bf16_f32 v5, v26, v28
	v_lshl_add_u64 v[36:37], v[30:31], 0, v[36:37]
	v_add_u32_e32 v6, 8, v38
	global_store_dwordx4 v[36:37], v[2:5], off
	v_cmp_lt_i32_e32 vcc, s18, v6
	s_waitcnt vmcnt(3)
	v_mov_b64_e32 v[48:49], v[60:61]
	v_cvt_pk_bf16_f32 v2, v13, v7
	v_add_u32_e32 v7, 0xffffea08, v38
	v_cndmask_b32_e32 v6, v6, v7, vcc
	v_lshlrev_b32_e32 v7, 1, v6
	v_and_b32_e32 v7, 0xffffff00, v7
	v_cndmask_b32_e32 v12, 0, v81, vcc
	v_and_b32_e32 v6, 0x6f, v6
	v_or3_b32 v6, v6, v12, v7
	v_ashrrev_i32_e32 v7, 31, v6
	v_lshlrev_b64 v[6:7], 12, v[6:7]
	v_cvt_pk_bf16_f32 v3, v15, v21
	v_cvt_pk_bf16_f32 v4, v23, v25
	v_cvt_pk_bf16_f32 v5, v27, v29
	v_lshl_add_u64 v[6:7], v[30:31], 0, v[6:7]
	ds_read2_b32 v[12:13], v77 offset0:16 offset1:24
	ds_read2_b32 v[14:15], v77 offset0:49 offset1:57
	ds_read2_b32 v[20:21], v77 offset0:82 offset1:90
	ds_read2_b32 v[22:23], v77 offset0:115 offset1:123
	ds_read2_b32 v[24:25], v77 offset0:148 offset1:156
	ds_read2_b32 v[26:27], v77 offset0:181 offset1:189
	ds_read2_b32 v[28:29], v77 offset0:214 offset1:222
	ds_read2_b32 v[36:37], v77 offset0:247 offset1:255
	global_store_dwordx4 v[6:7], v[2:5], off
	v_add_u32_e32 v6, 16, v38
	v_add_u32_e32 v7, 0xffffea10, v38
	v_cmp_lt_i32_e32 vcc, s18, v6
	s_waitcnt lgkmcnt(6)
	v_cvt_pk_bf16_f32 v2, v12, v14
	s_waitcnt lgkmcnt(4)
	v_cvt_pk_bf16_f32 v3, v20, v22
	v_cndmask_b32_e32 v6, v6, v7, vcc
	v_lshlrev_b32_e32 v7, 1, v6
	v_and_b32_e32 v7, 0xffffff00, v7
	v_cndmask_b32_e32 v12, 0, v81, vcc
	v_and_b32_e32 v6, 0x77, v6
	v_or3_b32 v6, v6, v12, v7
	v_ashrrev_i32_e32 v7, 31, v6
	v_lshlrev_b64 v[6:7], 12, v[6:7]
	s_waitcnt lgkmcnt(2)
	v_cvt_pk_bf16_f32 v4, v24, v26
	s_waitcnt lgkmcnt(0)
	v_cvt_pk_bf16_f32 v5, v28, v36
	v_lshl_add_u64 v[6:7], v[30:31], 0, v[6:7]
	global_store_dwordx4 v[6:7], v[2:5], off
	s_waitcnt vmcnt(4)
	v_mov_b64_e32 v[44:45], v[64:65]
	v_add_u32_e32 v83, s14, v83
	v_add_u32_e32 v2, 24, v38
	v_add_u32_e32 v3, 0xffffea18, v38
	v_cmp_lt_i32_e32 vcc, s18, v2
	v_cvt_pk_bf16_f32 v5, v29, v37
	v_mov_b64_e32 v[36:37], v[52:53]
	v_cndmask_b32_e32 v2, v2, v3, vcc
	v_lshlrev_b32_e32 v3, 1, v2
	v_and_b32_e32 v3, 0xffffff00, v3
	v_cndmask_b32_e32 v4, 0, v81, vcc
	v_and_b32_e32 v2, 0x7f, v2
	v_or3_b32 v6, v2, v4, v3
	v_ashrrev_i32_e32 v7, 31, v6
	v_lshlrev_b64 v[6:7], 12, v[6:7]
	v_cvt_pk_bf16_f32 v2, v13, v15
	v_cvt_pk_bf16_f32 v3, v21, v23
	v_cvt_pk_bf16_f32 v4, v25, v27
	v_lshl_add_u64 v[6:7], v[30:31], 0, v[6:7]
	global_store_dwordx4 v[6:7], v[2:5], off sc0 sc1
	s_waitcnt lgkmcnt(0)
	v_mov_b64_e32 v[12:13], v[16:17]
	v_mov_b64_e32 v[24:25], v[32:33]
	v_mov_b64_e32 v[4:5], v[8:9]
	v_mov_b64_e32 v[20:21], v[40:41]
	v_mov_b64_e32 v[28:29], v[56:57]
	s_add_i32 s19, s19, s14
	v_add_u32_e32 v73, s14, v73
	s_andn2_b64 vcc, exec, s[10:11]
	s_mov_b32 s6, s20
	v_mov_b64_e32 v[14:15], v[18:19]
	v_mov_b64_e32 v[6:7], v[10:11]
	v_mov_b64_e32 v[26:27], v[34:35]
	v_mov_b64_e32 v[22:23], v[42:43]
	v_mov_b64_e32 v[38:39], v[54:55]
	v_mov_b64_e32 v[30:31], v[58:59]
	v_mov_b64_e32 v[50:51], v[62:63]
	v_mov_b64_e32 v[46:47], v[66:67]
	v_mov_b32_e32 v72, v85
	v_mov_b32_e32 v74, v87
	v_mov_b32_e32 v76, v89
	v_mov_b32_e32 v78, v94
	v_mov_b32_e32 v80, v95
	v_mov_b32_e32 v82, v96
	v_mov_b32_e32 v84, v97
	s_waitcnt vmcnt(4)
	v_mov_b32_e32 v86, v1
	s_cbranch_vccz .LBB0_1862

; #define LAS __attribute__((address_space(3)))
; __device__ __forceinline__ unsigned cvtpk(float lo, float hi) { f32x2 v = {lo, hi}; bf16x2_t b = __builtin_convertvector(v, bf16x2_t); return __builtin_bit_cast(unsigned, b); }
; __device__ __forceinline__ void witem_store(const WItem& w, int K, bf16_t* WT, int kvperm, LAS float* scr, int item, int nblk, int lane) {
;     ...
;     for (int i = 0; i < 8; ++i) { LAS float* d = scr + (8 * i + rr) * 33 + col; const float g = w.g[i]; d[0] = w.v[i].x * g; d[1] = w.v[i].y * g; d[2] = w.v[i].z * g; d[3] = w.v[i].w * g; }
;     asm volatile("s_waitcnt lgkmcnt(0)" ::: "memory");
;     const int c = lane & 7;
; #pragma unroll
;     for (int j = 0; j < 4; ++j) { const int n = (lane >> 3) + 8 * j; const LAS float* s = scr + (8 * c) * 33 + n;
;         u32x4 o; o.x = cvtpk(s[0 * 33], s[1 * 33]); o.y = cvtpk(s[2 * 33], s[3 * 33]); o.z = cvtpk(s[4 * 33], s[5 * 33]); o.w = cvtpk(s[6 * 33], s[7 * 33]);
;         int nr = n0 + n; if (kvperm == 1) { const int hh = nr >> 8, ww = nr & 255; nr = (ww < 128) ? hh * 128 + ww : 2048 + hh * 128 + (ww - 128); }
;         else if (kvperm == 2) { const int isv = nr >= 5632, f = isv ? nr - 5632 : nr; nr = (f >> 7) * 256 + isv * 128 + (f & 127); }
;         *(u32x4*)(WT + (size_t)nr * K + k0 + 8 * c) = o; }
;     ...
;     while (it < i1) {
;         cur = nxt;
;         const int nit = it + NGW;
;         if (nit < i1) witem_load(nxt, W, N, gk, nit, nblk, lane);
;         witem_store(cur, K, WT, kvperm, scr, it, nblk, lane);
;         it = nit;
;     }
.LBB0_2334:
	v_pk_mul_f32 v[2:3], v[8:9], v[72:73] op_sel_hi:[1,0]
	ds_write2_b32 v79, v2, v3 offset1:1
	v_pk_mul_f32 v[2:3], v[10:11], v[72:73] op_sel_hi:[1,0]
	ds_write2_b32 v79, v2, v3 offset0:2 offset1:3
	v_pk_mul_f32 v[2:3], v[4:5], v[74:75] op_sel_hi:[1,0]
	v_add_u32_e32 v4, 0x420, v79
	ds_write2_b32 v4, v2, v3 offset1:1
	v_pk_mul_f32 v[2:3], v[6:7], v[74:75] op_sel_hi:[1,0]
	v_add_u32_e32 v4, 0x428, v79
	ds_write2_b32 v4, v2, v3 offset1:1
	v_pk_mul_f32 v[2:3], v[24:25], v[76:77] op_sel_hi:[1,0]
	v_add_u32_e32 v4, 0x840, v79
	ds_write2_b32 v4, v2, v3 offset1:1
	v_pk_mul_f32 v[2:3], v[26:27], v[76:77] op_sel_hi:[1,0]
	v_add_u32_e32 v4, 0x848, v79
	ds_write2_b32 v4, v2, v3 offset1:1
	v_pk_mul_f32 v[2:3], v[20:21], v[78:79] op_sel_hi:[1,0]
	v_add_u32_e32 v4, 0xc60, v79
	ds_write2_b32 v4, v2, v3 offset1:1
	v_pk_mul_f32 v[2:3], v[22:23], v[78:79] op_sel_hi:[1,0]
	v_add_u32_e32 v4, 0xc68, v79
	ds_write2_b32 v4, v2, v3 offset1:1
	v_pk_mul_f32 v[2:3], v[36:37], v[80:81] op_sel_hi:[1,0]
	v_add_u32_e32 v4, 0x1080, v79
	ds_write2_b32 v4, v2, v3 offset1:1
	v_pk_mul_f32 v[2:3], v[38:39], v[80:81] op_sel_hi:[1,0]
	v_add_u32_e32 v4, 0x1088, v79
	ds_write2_b32 v4, v2, v3 offset1:1
	v_pk_mul_f32 v[2:3], v[28:29], v[82:83] op_sel_hi:[1,0]
	v_add_u32_e32 v4, 0x14a0, v79
	ds_write2_b32 v4, v2, v3 offset1:1
	v_pk_mul_f32 v[2:3], v[30:31], v[82:83] op_sel_hi:[1,0]
	v_add_u32_e32 v4, 0x14a8, v79
	ds_write2_b32 v4, v2, v3 offset1:1
	s_waitcnt vmcnt(7)
	v_pk_mul_f32 v[2:3], v[48:49], v[84:85] op_sel_hi:[1,0]
	v_add_u32_e32 v4, 0x18c0, v79
	s_mul_hi_i32 s3, s3, 0x2e8ba2e9
	ds_write2_b32 v4, v2, v3 offset1:1
	v_pk_mul_f32 v[2:3], v[50:51], v[84:85] op_sel_hi:[1,0]
	v_add_u32_e32 v4, 0x18c8, v79
	s_lshr_b32 s8, s3, 31
	s_ashr_i32 s3, s3, 6
	ds_write2_b32 v4, v2, v3 offset1:1
	s_waitcnt vmcnt(6)
	v_pk_mul_f32 v[2:3], v[44:45], v[86:87] op_sel_hi:[1,0]
	v_add_u32_e32 v4, 0x1ce0, v79
	s_add_i32 s3, s3, s8
	ds_write2_b32 v4, v2, v3 offset1:1
	v_pk_mul_f32 v[2:3], v[46:47], v[86:87] op_sel_hi:[1,0]
	v_add_u32_e32 v4, 0x1ce8, v79
	s_lshl_b32 s8, s3, 6
	ds_write2_b32 v4, v2, v3 offset1:1
	s_mulk_i32 s3, 0xd400
	s_waitcnt lgkmcnt(0)
	s_add_i32 s3, s3, s6
	ds_read2_b32 v[6:7], v77 offset0:33 offset1:41
	ds_read2_b32 v[8:9], v77 offset1:8
	ds_read2_b32 v[10:11], v77 offset0:66 offset1:74
	ds_read2_b32 v[20:21], v77 offset0:99 offset1:107
	ds_read2_b32 v[22:23], v77 offset0:132 offset1:140
	ds_read2_b32 v[24:25], v77 offset0:165 offset1:173
	ds_read2_b32 v[26:27], v77 offset0:198 offset1:206
	ds_read2_b32 v[28:29], v77 offset0:231 offset1:239
	v_add_u32_e32 v38, s3, v83
	s_waitcnt lgkmcnt(6)
	v_cvt_pk_bf16_f32 v2, v8, v6
	v_add_u32_e32 v6, 0xffffea00, v38
	v_cmp_lt_i32_e32 vcc, s12, v38
	s_waitcnt lgkmcnt(4)
	v_cvt_pk_bf16_f32 v3, v10, v20
	s_ashr_i32 s9, s8, 31
	v_cndmask_b32_e32 v6, v38, v6, vcc
	v_lshlrev_b32_e32 v8, 1, v6
	v_and_b32_e32 v8, 0xffffff00, v8
	v_cndmask_b32_e32 v10, 0, v81, vcc
	v_and_b32_e32 v6, 0x67, v6
	v_or3_b32 v36, v6, v10, v8
	v_ashrrev_i32_e32 v37, 31, v36
	v_lshl_add_u64 v[30:31], s[8:9], 1, v[70:71]
	v_lshlrev_b64 v[36:37], 12, v[36:37]
	s_waitcnt lgkmcnt(2)
	v_cvt_pk_bf16_f32 v4, v22, v24
	s_waitcnt lgkmcnt(0)
	v_cvt_pk_bf16_f32 v5, v26, v28
	v_lshl_add_u64 v[36:37], v[30:31], 0, v[36:37]
	v_add_u32_e32 v6, 8, v38
	global_store_dwordx4 v[36:37], v[2:5], off
	v_cmp_lt_i32_e32 vcc, s12, v6
	s_waitcnt vmcnt(3)
	v_mov_b64_e32 v[48:49], v[60:61]
	v_cvt_pk_bf16_f32 v2, v9, v7
	v_add_u32_e32 v7, 0xffffea08, v38
	v_cndmask_b32_e32 v6, v6, v7, vcc
	v_lshlrev_b32_e32 v7, 1, v6
	v_and_b32_e32 v7, 0xffffff00, v7
	v_cndmask_b32_e32 v8, 0, v81, vcc
	v_and_b32_e32 v6, 0x6f, v6
	v_or3_b32 v6, v6, v8, v7
	v_ashrrev_i32_e32 v7, 31, v6
	v_lshlrev_b64 v[6:7], 12, v[6:7]
	v_cvt_pk_bf16_f32 v3, v11, v21
	v_cvt_pk_bf16_f32 v4, v23, v25
	v_cvt_pk_bf16_f32 v5, v27, v29
	v_lshl_add_u64 v[6:7], v[30:31], 0, v[6:7]
	ds_read2_b32 v[8:9], v77 offset0:16 offset1:24
	ds_read2_b32 v[10:11], v77 offset0:49 offset1:57
	ds_read2_b32 v[20:21], v77 offset0:82 offset1:90
	ds_read2_b32 v[22:23], v77 offset0:115 offset1:123
	ds_read2_b32 v[24:25], v77 offset0:148 offset1:156
	ds_read2_b32 v[26:27], v77 offset0:181 offset1:189
	ds_read2_b32 v[28:29], v77 offset0:214 offset1:222
	ds_read2_b32 v[36:37], v77 offset0:247 offset1:255
	global_store_dwordx4 v[6:7], v[2:5], off
	v_add_u32_e32 v6, 16, v38
	v_add_u32_e32 v7, 0xffffea10, v38
	v_cmp_lt_i32_e32 vcc, s12, v6
	s_waitcnt lgkmcnt(6)
	v_cvt_pk_bf16_f32 v2, v8, v10
	s_waitcnt lgkmcnt(4)
	v_cvt_pk_bf16_f32 v3, v20, v22
	v_cndmask_b32_e32 v6, v6, v7, vcc
	v_lshlrev_b32_e32 v7, 1, v6
	v_and_b32_e32 v7, 0xffffff00, v7
	v_cndmask_b32_e32 v8, 0, v81, vcc
	v_and_b32_e32 v6, 0x77, v6
	v_or3_b32 v6, v6, v8, v7
	v_ashrrev_i32_e32 v7, 31, v6
	v_lshlrev_b64 v[6:7], 12, v[6:7]
	s_waitcnt lgkmcnt(2)
	v_cvt_pk_bf16_f32 v4, v24, v26
	s_waitcnt lgkmcnt(0)
	v_cvt_pk_bf16_f32 v5, v28, v36
	v_lshl_add_u64 v[6:7], v[30:31], 0, v[6:7]
	global_store_dwordx4 v[6:7], v[2:5], off
	s_waitcnt vmcnt(4)
	v_mov_b64_e32 v[44:45], v[64:65]
	v_add_u32_e32 v83, s7, v83
	v_add_u32_e32 v2, 24, v38
	v_add_u32_e32 v3, 0xffffea18, v38
	v_cmp_lt_i32_e32 vcc, s12, v2
	v_cvt_pk_bf16_f32 v5, v29, v37
	v_mov_b64_e32 v[36:37], v[52:53]
	v_cndmask_b32_e32 v2, v2, v3, vcc
	v_lshlrev_b32_e32 v3, 1, v2
	v_and_b32_e32 v3, 0xffffff00, v3
	v_cndmask_b32_e32 v4, 0, v81, vcc
	v_and_b32_e32 v2, 0x7f, v2
	v_or3_b32 v6, v2, v4, v3
	v_ashrrev_i32_e32 v7, 31, v6
	v_lshlrev_b64 v[6:7], 12, v[6:7]
	v_cvt_pk_bf16_f32 v2, v9, v11
	v_cvt_pk_bf16_f32 v3, v21, v23
	v_cvt_pk_bf16_f32 v4, v25, v27
	v_lshl_add_u64 v[6:7], v[30:31], 0, v[6:7]
	global_store_dwordx4 v[6:7], v[2:5], off sc0 sc1
	s_waitcnt lgkmcnt(0)
	v_mov_b64_e32 v[8:9], v[16:17]
	v_mov_b64_e32 v[24:25], v[32:33]
	v_mov_b64_e32 v[4:5], v[12:13]
	v_mov_b64_e32 v[20:21], v[40:41]
	v_mov_b64_e32 v[28:29], v[56:57]
	s_add_i32 s13, s13, s7
	v_add_u32_e32 v73, s7, v73
	s_andn2_b64 vcc, exec, s[4:5]
	s_mov_b32 s3, s14
	v_mov_b64_e32 v[10:11], v[18:19]
	v_mov_b64_e32 v[6:7], v[14:15]
	v_mov_b64_e32 v[26:27], v[34:35]
	v_mov_b64_e32 v[22:23], v[42:43]
	v_mov_b64_e32 v[38:39], v[54:55]
	v_mov_b64_e32 v[30:31], v[58:59]
	v_mov_b64_e32 v[50:51], v[62:63]
	v_mov_b64_e32 v[46:47], v[66:67]
	v_mov_b32_e32 v72, v85
	v_mov_b32_e32 v74, v87
	v_mov_b32_e32 v76, v89
	v_mov_b32_e32 v78, v94
	v_mov_b32_e32 v80, v95
	v_mov_b32_e32 v82, v96
	v_mov_b32_e32 v84, v97
	s_waitcnt vmcnt(4)
	v_mov_b32_e32 v86, v1
	s_cbranch_vccz .LBB0_2352

; #define LAS __attribute__((address_space(3)))
; __device__ __forceinline__ unsigned cvtpk(float lo, float hi) { f32x2 v = {lo, hi}; bf16x2_t b = __builtin_convertvector(v, bf16x2_t); return __builtin_bit_cast(unsigned, b); }
; __device__ __forceinline__ void witem_store(const WItem& w, int K, bf16_t* WT, int kvperm, LAS float* scr, int item, int nblk, int lane) {
;     ...
;     for (int i = 0; i < 8; ++i) { LAS float* d = scr + (8 * i + rr) * 33 + col; const float g = w.g[i]; d[0] = w.v[i].x * g; d[1] = w.v[i].y * g; d[2] = w.v[i].z * g; d[3] = w.v[i].w * g; }
;     asm volatile("s_waitcnt lgkmcnt(0)" ::: "memory");
;     const int c = lane & 7;
; #pragma unroll
;     for (int j = 0; j < 4; ++j) { const int n = (lane >> 3) + 8 * j; const LAS float* s = scr + (8 * c) * 33 + n;
;         u32x4 o; o.x = cvtpk(s[0 * 33], s[1 * 33]); o.y = cvtpk(s[2 * 33], s[3 * 33]); o.z = cvtpk(s[4 * 33], s[5 * 33]); o.w = cvtpk(s[6 * 33], s[7 * 33]);
;         int nr = n0 + n; if (kvperm == 1) { const int hh = nr >> 8, ww = nr & 255; nr = (ww < 128) ? hh * 128 + ww : 2048 + hh * 128 + (ww - 128); }
;         else if (kvperm == 2) { const int isv = nr >= 5632, f = isv ? nr - 5632 : nr; nr = (f >> 7) * 256 + isv * 128 + (f & 127); }
;         *(u32x4*)(WT + (size_t)nr * K + k0 + 8 * c) = o; }
;     ...
;     while (it < i1) {
;         cur = nxt;
;         const int nit = it + NGW;
;         if (nit < i1) witem_load(nxt, W, N, gk, nit, nblk, lane);
;         witem_store(cur, K, WT, kvperm, scr, it, nblk, lane);
;         it = nit;
;     }
.LBB0_2612:
	v_pk_mul_f32 v[2:3], v[16:17], v[72:73] op_sel_hi:[1,0]
	ds_write2_b32 v79, v2, v3 offset1:1
	v_pk_mul_f32 v[2:3], v[18:19], v[72:73] op_sel_hi:[1,0]
	ds_write2_b32 v79, v2, v3 offset0:2 offset1:3
	v_pk_mul_f32 v[2:3], v[4:5], v[74:75] op_sel_hi:[1,0]
	v_add_u32_e32 v4, 0x420, v79
	ds_write2_b32 v4, v2, v3 offset1:1
	v_pk_mul_f32 v[2:3], v[6:7], v[74:75] op_sel_hi:[1,0]
	v_add_u32_e32 v4, 0x428, v79
	ds_write2_b32 v4, v2, v3 offset1:1
	v_pk_mul_f32 v[2:3], v[24:25], v[76:77] op_sel_hi:[1,0]
	v_add_u32_e32 v4, 0x840, v79
	ds_write2_b32 v4, v2, v3 offset1:1
	v_pk_mul_f32 v[2:3], v[26:27], v[76:77] op_sel_hi:[1,0]
	v_add_u32_e32 v4, 0x848, v79
	ds_write2_b32 v4, v2, v3 offset1:1
	v_pk_mul_f32 v[2:3], v[20:21], v[78:79] op_sel_hi:[1,0]
	v_add_u32_e32 v4, 0xc60, v79
	ds_write2_b32 v4, v2, v3 offset1:1
	v_pk_mul_f32 v[2:3], v[22:23], v[78:79] op_sel_hi:[1,0]
	v_add_u32_e32 v4, 0xc68, v79
	ds_write2_b32 v4, v2, v3 offset1:1
	v_pk_mul_f32 v[2:3], v[36:37], v[80:81] op_sel_hi:[1,0]
	v_add_u32_e32 v4, 0x1080, v79
	ds_write2_b32 v4, v2, v3 offset1:1
	v_pk_mul_f32 v[2:3], v[38:39], v[80:81] op_sel_hi:[1,0]
	v_add_u32_e32 v4, 0x1088, v79
	ds_write2_b32 v4, v2, v3 offset1:1
	v_pk_mul_f32 v[2:3], v[32:33], v[82:83] op_sel_hi:[1,0]
	v_add_u32_e32 v4, 0x14a0, v79
	s_mul_hi_i32 s8, s12, 0x2e8ba2e9
	ds_write2_b32 v4, v2, v3 offset1:1
	v_pk_mul_f32 v[2:3], v[34:35], v[82:83] op_sel_hi:[1,0]
	v_add_u32_e32 v4, 0x14a8, v79
	s_lshr_b32 s9, s8, 31
	s_ashr_i32 s8, s8, 6
	ds_write2_b32 v4, v2, v3 offset1:1
	s_waitcnt vmcnt(7)
	v_pk_mul_f32 v[2:3], v[48:49], v[84:85] op_sel_hi:[1,0]
	v_add_u32_e32 v4, 0x18c0, v79
	s_add_i32 s12, s8, s9
	ds_write2_b32 v4, v2, v3 offset1:1
	v_pk_mul_f32 v[2:3], v[50:51], v[84:85] op_sel_hi:[1,0]
	v_add_u32_e32 v4, 0x18c8, v79
	s_lshl_b32 s8, s12, 6
	ds_write2_b32 v4, v2, v3 offset1:1
	s_waitcnt vmcnt(6)
	v_pk_mul_f32 v[2:3], v[44:45], v[86:87] op_sel_hi:[1,0]
	v_add_u32_e32 v4, 0x1ce0, v79
	ds_write2_b32 v4, v2, v3 offset1:1
	v_pk_mul_f32 v[2:3], v[46:47], v[86:87] op_sel_hi:[1,0]
	v_add_u32_e32 v4, 0x1ce8, v79
	s_ashr_i32 s9, s8, 31
	ds_write2_b32 v4, v2, v3 offset1:1
	v_lshl_add_u64 v[34:35], s[8:9], 1, v[70:71]
	s_mul_i32 s8, s12, 0xffffd400
	s_waitcnt lgkmcnt(0)
	s_add_i32 s8, s8, s3
	ds_read2_b32 v[6:7], v75 offset0:33 offset1:41
	ds_read2_b32 v[16:17], v75 offset1:8
	ds_read2_b32 v[18:19], v75 offset0:66 offset1:74
	ds_read2_b32 v[20:21], v75 offset0:99 offset1:107
	ds_read2_b32 v[22:23], v75 offset0:132 offset1:140
	ds_read2_b32 v[24:25], v75 offset0:165 offset1:173
	ds_read2_b32 v[26:27], v75 offset0:198 offset1:206
	ds_read2_b32 v[32:33], v75 offset0:231 offset1:239
	v_add_u32_e32 v38, s8, v83
	s_waitcnt lgkmcnt(6)
	v_cvt_pk_bf16_f32 v2, v16, v6
	v_add_u32_e32 v6, 0xffffea00, v38
	v_cmp_lt_i32_e32 vcc, s11, v38
	s_waitcnt lgkmcnt(4)
	v_cvt_pk_bf16_f32 v3, v18, v20
	s_waitcnt lgkmcnt(2)
	v_cvt_pk_bf16_f32 v4, v22, v24
	v_cndmask_b32_e32 v6, v38, v6, vcc
	v_lshlrev_b32_e32 v16, 1, v6
	v_and_b32_e32 v16, 0xffffff00, v16
	v_cndmask_b32_e32 v18, 0, v81, vcc
	v_and_b32_e32 v6, 0x67, v6
	v_or3_b32 v36, v6, v18, v16
	v_ashrrev_i32_e32 v37, 31, v36
	v_lshlrev_b64 v[36:37], 12, v[36:37]
	s_waitcnt lgkmcnt(0)
	v_cvt_pk_bf16_f32 v5, v26, v32
	v_lshl_add_u64 v[36:37], v[34:35], 0, v[36:37]
	v_add_u32_e32 v6, 8, v38
	global_store_dwordx4 v[36:37], v[2:5], off
	v_cmp_lt_i32_e32 vcc, s11, v6
	s_waitcnt vmcnt(3)
	v_mov_b64_e32 v[48:49], v[60:61]
	v_cvt_pk_bf16_f32 v2, v17, v7
	v_add_u32_e32 v7, 0xffffea08, v38
	v_cndmask_b32_e32 v6, v6, v7, vcc
	v_lshlrev_b32_e32 v7, 1, v6
	v_and_b32_e32 v7, 0xffffff00, v7
	v_cndmask_b32_e32 v16, 0, v81, vcc
	v_and_b32_e32 v6, 0x6f, v6
	v_or3_b32 v6, v6, v16, v7
	v_ashrrev_i32_e32 v7, 31, v6
	v_lshlrev_b64 v[6:7], 12, v[6:7]
	v_cvt_pk_bf16_f32 v3, v19, v21
	v_cvt_pk_bf16_f32 v4, v23, v25
	v_cvt_pk_bf16_f32 v5, v27, v33
	v_lshl_add_u64 v[6:7], v[34:35], 0, v[6:7]
	ds_read2_b32 v[16:17], v75 offset0:16 offset1:24
	ds_read2_b32 v[18:19], v75 offset0:49 offset1:57
	ds_read2_b32 v[20:21], v75 offset0:82 offset1:90
	ds_read2_b32 v[22:23], v75 offset0:115 offset1:123
	ds_read2_b32 v[24:25], v75 offset0:148 offset1:156
	ds_read2_b32 v[26:27], v75 offset0:181 offset1:189
	ds_read2_b32 v[32:33], v75 offset0:214 offset1:222
	ds_read2_b32 v[36:37], v75 offset0:247 offset1:255
	global_store_dwordx4 v[6:7], v[2:5], off
	v_add_u32_e32 v6, 16, v38
	v_add_u32_e32 v7, 0xffffea10, v38
	v_cmp_lt_i32_e32 vcc, s11, v6
	s_waitcnt lgkmcnt(6)
	v_cvt_pk_bf16_f32 v2, v16, v18
	s_waitcnt lgkmcnt(4)
	v_cvt_pk_bf16_f32 v3, v20, v22
	v_cndmask_b32_e32 v6, v6, v7, vcc
	v_lshlrev_b32_e32 v7, 1, v6
	v_and_b32_e32 v7, 0xffffff00, v7
	v_cndmask_b32_e32 v16, 0, v81, vcc
	v_and_b32_e32 v6, 0x77, v6
	v_or3_b32 v6, v6, v16, v7
	v_ashrrev_i32_e32 v7, 31, v6
	v_lshlrev_b64 v[6:7], 12, v[6:7]
	s_waitcnt lgkmcnt(2)
	v_cvt_pk_bf16_f32 v4, v24, v26
	s_waitcnt lgkmcnt(0)
	v_cvt_pk_bf16_f32 v5, v32, v36
	v_lshl_add_u64 v[6:7], v[34:35], 0, v[6:7]
	global_store_dwordx4 v[6:7], v[2:5], off
	s_waitcnt vmcnt(4)
	v_mov_b64_e32 v[44:45], v[64:65]
	v_add_u32_e32 v83, s6, v83
	v_add_u32_e32 v2, 24, v38
	v_add_u32_e32 v3, 0xffffea18, v38
	v_cmp_lt_i32_e32 vcc, s11, v2
	v_cvt_pk_bf16_f32 v5, v33, v37
	v_mov_b64_e32 v[36:37], v[52:53]
	v_cndmask_b32_e32 v2, v2, v3, vcc
	v_lshlrev_b32_e32 v3, 1, v2
	v_and_b32_e32 v3, 0xffffff00, v3
	v_cndmask_b32_e32 v4, 0, v81, vcc
	v_and_b32_e32 v2, 0x7f, v2
	v_or3_b32 v6, v2, v4, v3
	v_ashrrev_i32_e32 v7, 31, v6
	v_lshlrev_b64 v[6:7], 12, v[6:7]
	v_cvt_pk_bf16_f32 v2, v17, v19
	v_cvt_pk_bf16_f32 v3, v21, v23
	v_cvt_pk_bf16_f32 v4, v25, v27
	v_lshl_add_u64 v[6:7], v[34:35], 0, v[6:7]
	global_store_dwordx4 v[6:7], v[2:5], off sc0 sc1
	s_waitcnt lgkmcnt(0)
	v_mov_b64_e32 v[18:19], v[14:15]
	v_mov_b64_e32 v[24:25], v[28:29]
	v_mov_b64_e32 v[4:5], v[8:9]
	v_mov_b64_e32 v[20:21], v[40:41]
	v_mov_b64_e32 v[32:33], v[56:57]
	s_add_i32 s13, s13, s6
	v_add_u32_e32 v73, s6, v73
	s_andn2_b64 vcc, exec, s[0:1]
	s_mov_b32 s12, s14
	v_mov_b64_e32 v[16:17], v[12:13]
	v_mov_b64_e32 v[6:7], v[10:11]
	v_mov_b64_e32 v[26:27], v[30:31]
	v_mov_b64_e32 v[22:23], v[42:43]
	v_mov_b64_e32 v[38:39], v[54:55]
	v_mov_b64_e32 v[34:35], v[58:59]
	v_mov_b64_e32 v[50:51], v[62:63]
	v_mov_b64_e32 v[46:47], v[66:67]
	v_mov_b32_e32 v72, v85
	v_mov_b32_e32 v74, v87
	v_mov_b32_e32 v76, v89
	v_mov_b32_e32 v78, v94
	v_mov_b32_e32 v80, v95
	v_mov_b32_e32 v82, v96
	v_mov_b32_e32 v84, v97
	s_waitcnt vmcnt(4)
	v_mov_b32_e32 v86, v1
	s_cbranch_vccz .LBB0_2630
